# ffn_in: the ai=1 half of the SwiGLU epilogue runs in the load slot of the next unit's first super-phase; the two epilogue-alignment barriers per unit are gone
# baseline (speedup 1.0000x reference)
.Lwgm_orig_0:
	s_ashr_i32 s22, s28, 31
	s_lshr_b32 s22, s22, 29
	s_add_i32 s22, s28, s22
	s_ashr_i32 s23, s22, 3
	s_and_b32 s22, s22, -8
	s_sub_i32 s22, s28, s22
	s_cmp_lt_i32 s22, 0
	s_cselect_b32 s26, s54, 0x160
	s_mul_i32 s22, s26, s22
	s_add_i32 s22, s22, s23
	s_mul_hi_i32 s23, s22, 0x2e8ba2e9
	s_lshr_b32 s26, s23, 31
	s_ashr_i32 s23, s23, 3
	s_add_i32 s23, s23, s26
	s_lshl_b32 s26, s23, 1
	s_sub_i32 s27, 0x80, s26
	s_min_i32 s27, s27, 2
	s_abs_i32 s28, s27
	v_cvt_f32_u32_e32 v250, s28
	s_sub_i32 s30, 0, s28
	s_mul_i32 s23, s23, 44
	s_sub_i32 s23, s22, s23
	v_rcp_iflag_f32_e32 v250, v250
	s_abs_i32 s22, s23
	s_xor_b32 s29, s23, s27
	s_ashr_i32 s29, s29, 31
	v_mul_f32_e32 v250, 0x4f7ffffe, v250
	v_cvt_u32_f32_e32 v250, v250
	s_nop 0
	v_readfirstlane_b32 s31, v250
	s_mul_i32 s30, s30, s31
	s_mul_hi_u32 s30, s31, s30
	s_add_i32 s31, s31, s30
	s_mul_hi_u32 s30, s22, s31
	s_mul_i32 s31, s30, s28
	s_sub_i32 s22, s22, s31
	s_add_i32 s45, s30, 1
	s_sub_i32 s31, s22, s28
	s_cmp_ge_u32 s22, s28
	s_cselect_b32 s30, s45, s30
	s_cselect_b32 s22, s31, s22
	s_add_i32 s31, s30, 1
	s_cmp_ge_u32 s22, s28
	s_cselect_b32 s22, s31, s30
	s_xor_b32 s22, s22, s29
	s_sub_i32 s22, s22, s29
	s_mul_i32 s27, s22, s27
	s_sub_i32 s23, s23, s27
	s_add_i32 s26, s23, s26
.LBB0_74:
	s_ashr_i32 s27, s26, 31
	s_lshl_b64 s[28:29], s[26:27], 19
	s_add_u32 s28, s3, s28
	s_addc_u32 s29, s35, s29
	s_and_b64 s[30:31], s[4:5], exec
	s_cselect_b32 s27, s29, s49
	s_cselect_b32 s68, s28, s48
	s_ashr_i32 s23, s22, 31
	s_lshl_b64 s[30:31], s[22:23], 19
	s_add_u32 s30, s50, s30
	s_addc_u32 s31, s51, s31
	s_and_b64 s[70:71], s[4:5], exec
	s_cselect_b32 s69, s31, s47
	s_cselect_b32 s70, s30, s46
	s_lshl_b32 s23, s44, 8
	v_add_u32_e32 v250, s23, v148
	s_add_u32 s71, s46, 0x100
	v_ashrrev_i32_e32 v251, 31, v250
	s_addc_u32 s74, s47, 0
	v_lshl_add_u64 v[144:145], v[250:251], 4, s[12:13]
	s_add_u32 s44, s48, 0x40080
	s_addc_u32 s45, s49, 0
	s_mov_b32 s75, -2
	s_mov_b64 s[46:47], 0
	s_cmp_eq_u32 s59, 1
	s_cbranch_scc1 .Lfa_0
	v_add_u32_e32 v153, s64, v147
	ds_read_b128 v[160:163], v153
	v_xor_b32_e32 v253, 64, v153
	ds_read_b128 v[164:167], v253
	ds_read_b128 v[168:171], v153 offset:2048
	ds_read_b128 v[172:175], v253 offset:2048
	v_add_u32_e32 v153, s65, v147
	ds_read_b128 v[176:179], v153
	v_xor_b32_e32 v253, 64, v153
	ds_read_b128 v[180:183], v253
	ds_read_b128 v[186:189], v153 offset:2048
	ds_read_b128 v[190:193], v253 offset:2048
	s_add_u32 s48, s44, 0xfffc0080
	s_addc_u32 s49, s45, -1
	s_and_b64 s[46:47], s[46:47], exec
	s_cselect_b32 s49, s27, s49
	s_cselect_b32 s48, s68, s48
	s_cselect_b32 s47, s69, s74
	s_cselect_b32 s46, s70, s71
	v_lshl_add_u64 v[154:155], s[44:45], 0, v[138:139]
	s_add_i32 m0, s55, 0xc000
	ds_read_b128 v[194:197], v150
	v_xor_b32_e32 v253, 64, v150
	ds_read_b128 v[198:201], v253
	ds_read_b128 v[202:205], v150 offset:2048
	ds_read_b128 v[206:209], v253 offset:2048
	ds_read_b128 v[210:213], v150 offset:4096
	ds_read_b128 v[214:217], v253 offset:4096
	ds_read_b128 v[218:221], v150 offset:6144
	ds_read_b128 v[222:225], v253 offset:6144
	global_load_lds_dwordx4 v[154:155], off
	v_lshl_add_u64 v[154:155], s[44:45], 0, v[136:137]
	s_add_i32 m0, s55, 0xe000
	s_nop 0
	global_load_lds_dwordx4 v[154:155], off
	s_waitcnt lgkmcnt(0)
	v_add_u32_e32 v235, 0x84000, v235
	v_add_u32_e32 v234, 0x21800, v151
	ds_read_b128 v[236:239], v234
	ds_read_b128 v[240:243], v234 offset:256
	ds_read_b128 v[244:247], v234 offset:512
	ds_read_b128 v[248:251], v234 offset:768
	s_waitcnt lgkmcnt(0)
	v_add_f32_e32 v236, v236, v237
	v_add_f32_e32 v238, v238, v239
	v_add_f32_e32 v240, v240, v241
	v_add_f32_e32 v242, v242, v243
	v_add_f32_e32 v244, v244, v245
	v_add_f32_e32 v246, v246, v247
	v_add_f32_e32 v248, v248, v249
	v_add_f32_e32 v250, v250, v251
	v_add_f32_e32 v236, v236, v238
	v_add_f32_e32 v240, v240, v242
	v_add_f32_e32 v244, v244, v246
	v_add_f32_e32 v248, v248, v250
	v_fmamk_f32 v236, v236, 0x3a800000, v152
	v_fmamk_f32 v240, v240, 0x3a800000, v152
	v_fmamk_f32 v244, v244, 0x3a800000, v152
	v_fmamk_f32 v248, v248, 0x3a800000, v152
	v_rsq_f32_e32 v236, v236
	v_rsq_f32_e32 v240, v240
	v_rsq_f32_e32 v244, v244
	v_rsq_f32_e32 v248, v248
	v_mul_f32_e32 v252, 0xbfb8aa3b, v236
	v_mul_f32_e32 v254, v236, v236
	v_rcp_f32_e32 v254, v254
	v_pk_mul_f32 v[56:57], v[60:61], v[56:57]
	v_pk_mul_f32 v[58:59], v[62:63], v[58:59]
	v_pk_mul_f32 v[48:49], v[52:53], v[48:49]
	v_pk_mul_f32 v[50:51], v[54:55], v[50:51]
	v_pk_mul_f32 v[60:61], v[60:61], v[252:253] op_sel_hi:[1,0]
	v_pk_mul_f32 v[62:63], v[62:63], v[252:253] op_sel_hi:[1,0]
	v_pk_mul_f32 v[52:53], v[52:53], v[252:253] op_sel_hi:[1,0]
	v_pk_mul_f32 v[54:55], v[54:55], v[252:253] op_sel_hi:[1,0]
	v_exp_f32_e32 v60, v60
	v_exp_f32_e32 v61, v61
	v_exp_f32_e32 v62, v62
	v_exp_f32_e32 v63, v63
	v_exp_f32_e32 v52, v52
	v_exp_f32_e32 v53, v53
	v_exp_f32_e32 v54, v54
	v_exp_f32_e32 v55, v55
	v_pk_fma_f32 v[60:61], v[60:61], v[254:255], v[254:255] op_sel_hi:[1,0,0]
	v_pk_fma_f32 v[62:63], v[62:63], v[254:255], v[254:255] op_sel_hi:[1,0,0]
	v_pk_fma_f32 v[52:53], v[52:53], v[254:255], v[254:255] op_sel_hi:[1,0,0]
	v_pk_fma_f32 v[54:55], v[54:55], v[254:255], v[254:255] op_sel_hi:[1,0,0]
	v_rcp_f32_e32 v60, v60
	v_rcp_f32_e32 v61, v61
	v_rcp_f32_e32 v62, v62
	v_rcp_f32_e32 v63, v63
	v_rcp_f32_e32 v52, v52
	v_rcp_f32_e32 v53, v53
	v_rcp_f32_e32 v54, v54
	v_rcp_f32_e32 v55, v55
	v_pk_mul_f32 v[56:57], v[56:57], v[60:61]
	v_pk_mul_f32 v[58:59], v[58:59], v[62:63]
	v_pk_mul_f32 v[48:49], v[48:49], v[52:53]
	v_pk_mul_f32 v[50:51], v[50:51], v[54:55]
	v_cvt_pk_bf16_f32 v56, v56, v57
	v_cvt_pk_bf16_f32 v57, v58, v59
	v_cvt_pk_bf16_f32 v58, v48, v49
	v_cvt_pk_bf16_f32 v59, v50, v51
	global_store_dwordx4 v235, v[56:59], s[10:11]
	v_add_u32_e32 v234, 0x16000, v235
	v_mul_f32_e32 v252, 0xbfb8aa3b, v240
	v_mul_f32_e32 v254, v240, v240
	v_rcp_f32_e32 v254, v254
	v_pk_mul_f32 v[40:41], v[44:45], v[40:41]
	v_pk_mul_f32 v[42:43], v[46:47], v[42:43]
	v_pk_mul_f32 v[32:33], v[36:37], v[32:33]
	v_pk_mul_f32 v[34:35], v[38:39], v[34:35]
	v_pk_mul_f32 v[44:45], v[44:45], v[252:253] op_sel_hi:[1,0]
	v_pk_mul_f32 v[46:47], v[46:47], v[252:253] op_sel_hi:[1,0]
	v_pk_mul_f32 v[36:37], v[36:37], v[252:253] op_sel_hi:[1,0]
	v_pk_mul_f32 v[38:39], v[38:39], v[252:253] op_sel_hi:[1,0]
	v_exp_f32_e32 v44, v44
	v_exp_f32_e32 v45, v45
	v_exp_f32_e32 v46, v46
	v_exp_f32_e32 v47, v47
	v_exp_f32_e32 v36, v36
	v_exp_f32_e32 v37, v37
	v_exp_f32_e32 v38, v38
	v_exp_f32_e32 v39, v39
	v_pk_fma_f32 v[44:45], v[44:45], v[254:255], v[254:255] op_sel_hi:[1,0,0]
	v_pk_fma_f32 v[46:47], v[46:47], v[254:255], v[254:255] op_sel_hi:[1,0,0]
	v_pk_fma_f32 v[36:37], v[36:37], v[254:255], v[254:255] op_sel_hi:[1,0,0]
	v_pk_fma_f32 v[38:39], v[38:39], v[254:255], v[254:255] op_sel_hi:[1,0,0]
	v_rcp_f32_e32 v44, v44
	v_rcp_f32_e32 v45, v45
	v_rcp_f32_e32 v46, v46
	v_rcp_f32_e32 v47, v47
	v_rcp_f32_e32 v36, v36
	v_rcp_f32_e32 v37, v37
	v_rcp_f32_e32 v38, v38
	v_rcp_f32_e32 v39, v39
	v_pk_mul_f32 v[40:41], v[40:41], v[44:45]
	v_pk_mul_f32 v[42:43], v[42:43], v[46:47]
	v_pk_mul_f32 v[32:33], v[32:33], v[36:37]
	v_pk_mul_f32 v[34:35], v[34:35], v[38:39]
	v_cvt_pk_bf16_f32 v40, v40, v41
	v_cvt_pk_bf16_f32 v41, v42, v43
	v_cvt_pk_bf16_f32 v42, v32, v33
	v_cvt_pk_bf16_f32 v43, v34, v35
	global_store_dwordx4 v234, v[40:43], s[10:11]
	v_add_u32_e32 v235, 0x16000, v234
	v_mul_f32_e32 v252, 0xbfb8aa3b, v244
	v_mul_f32_e32 v254, v244, v244
	v_rcp_f32_e32 v254, v254
	v_pk_mul_f32 v[24:25], v[28:29], v[24:25]
	v_pk_mul_f32 v[26:27], v[30:31], v[26:27]
	v_pk_mul_f32 v[16:17], v[20:21], v[16:17]
	v_pk_mul_f32 v[18:19], v[22:23], v[18:19]
	v_pk_mul_f32 v[28:29], v[28:29], v[252:253] op_sel_hi:[1,0]
	v_pk_mul_f32 v[30:31], v[30:31], v[252:253] op_sel_hi:[1,0]
	v_pk_mul_f32 v[20:21], v[20:21], v[252:253] op_sel_hi:[1,0]
	v_pk_mul_f32 v[22:23], v[22:23], v[252:253] op_sel_hi:[1,0]
	v_exp_f32_e32 v28, v28
	v_exp_f32_e32 v29, v29
	v_exp_f32_e32 v30, v30
	v_exp_f32_e32 v31, v31
	v_exp_f32_e32 v20, v20
	v_exp_f32_e32 v21, v21
	v_exp_f32_e32 v22, v22
	v_exp_f32_e32 v23, v23
	v_pk_fma_f32 v[28:29], v[28:29], v[254:255], v[254:255] op_sel_hi:[1,0,0]
	v_pk_fma_f32 v[30:31], v[30:31], v[254:255], v[254:255] op_sel_hi:[1,0,0]
	v_pk_fma_f32 v[20:21], v[20:21], v[254:255], v[254:255] op_sel_hi:[1,0,0]
	v_pk_fma_f32 v[22:23], v[22:23], v[254:255], v[254:255] op_sel_hi:[1,0,0]
	v_rcp_f32_e32 v28, v28
	v_rcp_f32_e32 v29, v29
	v_rcp_f32_e32 v30, v30
	v_rcp_f32_e32 v31, v31
	v_rcp_f32_e32 v20, v20
	v_rcp_f32_e32 v21, v21
	v_rcp_f32_e32 v22, v22
	v_rcp_f32_e32 v23, v23
	v_pk_mul_f32 v[24:25], v[24:25], v[28:29]
	v_pk_mul_f32 v[26:27], v[26:27], v[30:31]
	v_pk_mul_f32 v[16:17], v[16:17], v[20:21]
	v_pk_mul_f32 v[18:19], v[18:19], v[22:23]
	v_cvt_pk_bf16_f32 v24, v24, v25
	v_cvt_pk_bf16_f32 v25, v26, v27
	v_cvt_pk_bf16_f32 v26, v16, v17
	v_cvt_pk_bf16_f32 v27, v18, v19
	global_store_dwordx4 v235, v[24:27], s[10:11]
	v_add_u32_e32 v234, 0x16000, v235
	v_mul_f32_e32 v252, 0xbfb8aa3b, v248
	v_mul_f32_e32 v254, v248, v248
	v_rcp_f32_e32 v254, v254
	v_pk_mul_f32 v[8:9], v[12:13], v[8:9]
	v_pk_mul_f32 v[10:11], v[14:15], v[10:11]
	v_pk_mul_f32 v[0:1], v[4:5], v[0:1]
	v_pk_mul_f32 v[2:3], v[6:7], v[2:3]
	v_pk_mul_f32 v[12:13], v[12:13], v[252:253] op_sel_hi:[1,0]
	v_pk_mul_f32 v[14:15], v[14:15], v[252:253] op_sel_hi:[1,0]
	v_pk_mul_f32 v[4:5], v[4:5], v[252:253] op_sel_hi:[1,0]
	v_pk_mul_f32 v[6:7], v[6:7], v[252:253] op_sel_hi:[1,0]
	v_exp_f32_e32 v12, v12
	v_exp_f32_e32 v13, v13
	v_exp_f32_e32 v14, v14
	v_exp_f32_e32 v15, v15
	v_exp_f32_e32 v4, v4
	v_exp_f32_e32 v5, v5
	v_exp_f32_e32 v6, v6
	v_exp_f32_e32 v7, v7
	v_pk_fma_f32 v[12:13], v[12:13], v[254:255], v[254:255] op_sel_hi:[1,0,0]
	v_pk_fma_f32 v[14:15], v[14:15], v[254:255], v[254:255] op_sel_hi:[1,0,0]
	v_pk_fma_f32 v[4:5], v[4:5], v[254:255], v[254:255] op_sel_hi:[1,0,0]
	v_pk_fma_f32 v[6:7], v[6:7], v[254:255], v[254:255] op_sel_hi:[1,0,0]
	v_rcp_f32_e32 v12, v12
	v_rcp_f32_e32 v13, v13
	v_rcp_f32_e32 v14, v14
	v_rcp_f32_e32 v15, v15
	v_rcp_f32_e32 v4, v4
	v_rcp_f32_e32 v5, v5
	v_rcp_f32_e32 v6, v6
	v_rcp_f32_e32 v7, v7
	v_pk_mul_f32 v[8:9], v[8:9], v[12:13]
	v_pk_mul_f32 v[10:11], v[10:11], v[14:15]
	v_pk_mul_f32 v[0:1], v[0:1], v[4:5]
	v_pk_mul_f32 v[2:3], v[2:3], v[6:7]
	v_cvt_pk_bf16_f32 v8, v8, v9
	v_cvt_pk_bf16_f32 v9, v10, v11
	v_cvt_pk_bf16_f32 v10, v0, v1
	v_cvt_pk_bf16_f32 v11, v2, v3
	global_store_dwordx4 v234, v[8:11], s[10:11]
	s_waitcnt vmcnt(16)
	s_waitcnt lgkmcnt(0)
	s_barrier
	s_setprio 1
	s_waitcnt lgkmcnt(0)
	v_mfma_f32_16x16x32_bf16 v[124:127], v[160:163], v[194:197], 0
	v_mfma_f32_16x16x32_bf16 v[116:119], v[168:171], v[194:197], 0
	v_mfma_f32_16x16x32_bf16 v[108:111], v[160:163], v[202:205], 0
	v_mfma_f32_16x16x32_bf16 v[100:103], v[168:171], v[202:205], 0
	v_mfma_f32_16x16x32_bf16 v[92:95], v[160:163], v[210:213], 0
	v_mfma_f32_16x16x32_bf16 v[84:87], v[168:171], v[210:213], 0
	v_mfma_f32_16x16x32_bf16 v[76:79], v[160:163], v[218:221], 0
	v_mfma_f32_16x16x32_bf16 v[68:71], v[168:171], v[218:221], 0
	v_mfma_f32_16x16x32_bf16 v[124:127], v[164:167], v[198:201], v[124:127]
	v_mfma_f32_16x16x32_bf16 v[116:119], v[172:175], v[198:201], v[116:119]
	v_mfma_f32_16x16x32_bf16 v[108:111], v[164:167], v[206:209], v[108:111]
	v_mfma_f32_16x16x32_bf16 v[100:103], v[172:175], v[206:209], v[100:103]
	v_mfma_f32_16x16x32_bf16 v[92:95], v[164:167], v[214:217], v[92:95]
	v_mfma_f32_16x16x32_bf16 v[84:87], v[172:175], v[214:217], v[84:87]
	v_mfma_f32_16x16x32_bf16 v[76:79], v[164:167], v[222:225], v[76:79]
	v_mfma_f32_16x16x32_bf16 v[68:71], v[172:175], v[222:225], v[68:71]
	s_setprio 0
	s_setprio 1
	v_mfma_f32_16x16x32_bf16 v[120:123], v[176:179], v[194:197], 0
	v_mfma_f32_16x16x32_bf16 v[112:115], v[186:189], v[194:197], 0
	v_mfma_f32_16x16x32_bf16 v[104:107], v[176:179], v[202:205], 0
	v_mfma_f32_16x16x32_bf16 v[96:99], v[186:189], v[202:205], 0
	v_mfma_f32_16x16x32_bf16 v[88:91], v[176:179], v[210:213], 0
	v_mfma_f32_16x16x32_bf16 v[80:83], v[186:189], v[210:213], 0
	v_mfma_f32_16x16x32_bf16 v[72:75], v[176:179], v[218:221], 0
	v_mfma_f32_16x16x32_bf16 v[64:67], v[186:189], v[218:221], 0
	v_mfma_f32_16x16x32_bf16 v[120:123], v[180:183], v[198:201], v[120:123]
	v_mfma_f32_16x16x32_bf16 v[112:115], v[190:193], v[198:201], v[112:115]
	v_mfma_f32_16x16x32_bf16 v[104:107], v[180:183], v[206:209], v[104:107]
	v_mfma_f32_16x16x32_bf16 v[96:99], v[190:193], v[206:209], v[96:99]
	v_mfma_f32_16x16x32_bf16 v[88:91], v[180:183], v[214:217], v[88:91]
	v_mfma_f32_16x16x32_bf16 v[80:83], v[190:193], v[214:217], v[80:83]
	v_mfma_f32_16x16x32_bf16 v[72:75], v[180:183], v[222:225], v[72:75]
	v_mfma_f32_16x16x32_bf16 v[64:67], v[190:193], v[222:225], v[64:67]
	s_setprio 0
	s_barrier
	s_add_i32 s76, s64, s52
	v_lshl_add_u64 v[154:155], s[46:47], 0, v[132:133]
	s_mov_b32 m0, s76
	ds_read_b128 v[194:197], v150 offset:16384
	v_xor_b32_e32 v253, 64, v150
	ds_read_b128 v[198:201], v253 offset:16384
	ds_read_b128 v[202:205], v150 offset:18432
	ds_read_b128 v[206:209], v253 offset:18432
	ds_read_b128 v[210:213], v150 offset:20480
	ds_read_b128 v[214:217], v253 offset:20480
	ds_read_b128 v[218:221], v150 offset:22528
	ds_read_b128 v[222:225], v253 offset:22528
	global_load_lds_dwordx4 v[154:155], off
	s_add_i32 m0, s76, 0x2000
	s_add_u32 s76, s46, 0x40000
	v_lshl_add_u64 v[226:227], s[46:47], 0, v[128:129]
	s_addc_u32 s77, s47, 0
	s_add_i32 s78, s65, s52
	global_load_lds_dwordx4 v[226:227], off
	v_lshl_add_u64 v[228:229], s[76:77], 0, v[132:133]
	s_mov_b32 m0, s78
	v_lshl_add_u64 v[230:231], s[48:49], 0, v[130:131]
	global_load_lds_dwordx4 v[228:229], off
	v_lshl_add_u64 v[228:229], s[76:77], 0, v[128:129]
	s_add_i32 m0, s78, 0x2000
	s_nop 0
	global_load_lds_dwordx4 v[228:229], off
	v_lshl_add_u64 v[228:229], s[48:49], 0, v[134:135]
	s_mov_b32 m0, s55
	s_nop 0
	global_load_lds_dwordx4 v[228:229], off
	s_mov_b32 m0, s56
	s_nop 0
	global_load_lds_dwordx4 v[230:231], off
	s_waitcnt vmcnt(16)
	s_waitcnt lgkmcnt(0)
	s_barrier
	s_setprio 1
	s_waitcnt lgkmcnt(0)
	v_mfma_f32_16x16x32_bf16 v[60:63], v[160:163], v[194:197], 0
	v_mfma_f32_16x16x32_bf16 v[52:55], v[168:171], v[194:197], 0
	v_mfma_f32_16x16x32_bf16 v[44:47], v[160:163], v[202:205], 0
	v_mfma_f32_16x16x32_bf16 v[36:39], v[168:171], v[202:205], 0
	v_mfma_f32_16x16x32_bf16 v[28:31], v[160:163], v[210:213], 0
	v_mfma_f32_16x16x32_bf16 v[20:23], v[168:171], v[210:213], 0
	v_mfma_f32_16x16x32_bf16 v[12:15], v[160:163], v[218:221], 0
	v_mfma_f32_16x16x32_bf16 v[4:7], v[168:171], v[218:221], 0
	v_mfma_f32_16x16x32_bf16 v[60:63], v[164:167], v[198:201], v[60:63]
	v_mfma_f32_16x16x32_bf16 v[52:55], v[172:175], v[198:201], v[52:55]
	v_mfma_f32_16x16x32_bf16 v[44:47], v[164:167], v[206:209], v[44:47]
	v_mfma_f32_16x16x32_bf16 v[36:39], v[172:175], v[206:209], v[36:39]
	v_mfma_f32_16x16x32_bf16 v[28:31], v[164:167], v[214:217], v[28:31]
	v_mfma_f32_16x16x32_bf16 v[20:23], v[172:175], v[214:217], v[20:23]
	v_mfma_f32_16x16x32_bf16 v[12:15], v[164:167], v[222:225], v[12:15]
	v_mfma_f32_16x16x32_bf16 v[4:7], v[172:175], v[222:225], v[4:7]
	s_setprio 0
	s_setprio 1
	v_mfma_f32_16x16x32_bf16 v[56:59], v[176:179], v[194:197], 0
	v_mfma_f32_16x16x32_bf16 v[48:51], v[186:189], v[194:197], 0
	v_mfma_f32_16x16x32_bf16 v[40:43], v[176:179], v[202:205], 0
	v_mfma_f32_16x16x32_bf16 v[32:35], v[186:189], v[202:205], 0
	v_mfma_f32_16x16x32_bf16 v[24:27], v[176:179], v[210:213], 0
	v_mfma_f32_16x16x32_bf16 v[16:19], v[186:189], v[210:213], 0
	v_mfma_f32_16x16x32_bf16 v[8:11], v[176:179], v[218:221], 0
	v_mfma_f32_16x16x32_bf16 v[0:3], v[186:189], v[218:221], 0
	v_mfma_f32_16x16x32_bf16 v[56:59], v[180:183], v[198:201], v[56:59]
	v_mfma_f32_16x16x32_bf16 v[48:51], v[190:193], v[198:201], v[48:51]
	v_mfma_f32_16x16x32_bf16 v[40:43], v[180:183], v[206:209], v[40:43]
	v_mfma_f32_16x16x32_bf16 v[32:35], v[190:193], v[206:209], v[32:35]
	v_mfma_f32_16x16x32_bf16 v[24:27], v[180:183], v[214:217], v[24:27]
	v_mfma_f32_16x16x32_bf16 v[16:19], v[190:193], v[214:217], v[16:19]
	v_mfma_f32_16x16x32_bf16 v[8:11], v[180:183], v[222:225], v[8:11]
	v_mfma_f32_16x16x32_bf16 v[0:3], v[190:193], v[222:225], v[0:3]
	s_setprio 0
	s_barrier
	s_add_i32 s76, 0, 0x18000
	v_add_u32_e32 v153, s76, v147
	s_add_i32 s77, 0, 0x1c000
	ds_read_b128 v[160:163], v153
	v_xor_b32_e32 v253, 64, v153
	ds_read_b128 v[164:167], v253
	ds_read_b128 v[168:171], v153 offset:2048
	ds_read_b128 v[172:175], v253 offset:2048
	v_add_u32_e32 v153, s77, v147
	ds_read_b128 v[176:179], v153
	v_xor_b32_e32 v253, 64, v153
	ds_read_b128 v[180:183], v253
	ds_read_b128 v[186:189], v153 offset:2048
	ds_read_b128 v[190:193], v253 offset:2048
	s_add_u32 s48, s48, 0x40000
	s_addc_u32 s49, s49, 0
	s_mov_b32 m0, s57
	v_lshl_add_u64 v[232:233], s[48:49], 0, v[134:135]
	ds_read_b128 v[194:197], v150 offset:32768
	v_xor_b32_e32 v253, 64, v150
	ds_read_b128 v[198:201], v253 offset:32768
	ds_read_b128 v[202:205], v150 offset:34816
	ds_read_b128 v[206:209], v253 offset:34816
	ds_read_b128 v[210:213], v150 offset:36864
	ds_read_b128 v[214:217], v253 offset:36864
	ds_read_b128 v[218:221], v150 offset:38912
	ds_read_b128 v[222:225], v253 offset:38912
	global_load_lds_dwordx4 v[232:233], off
	v_lshl_add_u64 v[232:233], s[48:49], 0, v[130:131]
	s_mov_b32 m0, s58
	s_nop 0
	global_load_lds_dwordx4 v[232:233], off
	s_waitcnt vmcnt(12)
	s_waitcnt lgkmcnt(0)
	s_barrier
	s_setprio 1
	s_waitcnt lgkmcnt(0)
	v_mfma_f32_16x16x32_bf16 v[124:127], v[160:163], v[194:197], v[124:127]
	v_mfma_f32_16x16x32_bf16 v[124:127], v[164:167], v[198:201], v[124:127]
	v_mfma_f32_16x16x32_bf16 v[116:119], v[172:175], v[198:201], v[116:119]
	v_mfma_f32_16x16x32_bf16 v[116:119], v[168:171], v[194:197], v[116:119]
	v_mfma_f32_16x16x32_bf16 v[100:103], v[168:171], v[202:205], v[100:103]
	v_mfma_f32_16x16x32_bf16 v[100:103], v[172:175], v[206:209], v[100:103]
	v_mfma_f32_16x16x32_bf16 v[108:111], v[164:167], v[206:209], v[108:111]
	v_mfma_f32_16x16x32_bf16 v[108:111], v[160:163], v[202:205], v[108:111]
	v_mfma_f32_16x16x32_bf16 v[92:95], v[160:163], v[210:213], v[92:95]
	v_mfma_f32_16x16x32_bf16 v[92:95], v[164:167], v[214:217], v[92:95]
	v_mfma_f32_16x16x32_bf16 v[84:87], v[172:175], v[214:217], v[84:87]
	v_mfma_f32_16x16x32_bf16 v[84:87], v[168:171], v[210:213], v[84:87]
	v_mfma_f32_16x16x32_bf16 v[68:71], v[168:171], v[218:221], v[68:71]
	v_mfma_f32_16x16x32_bf16 v[68:71], v[172:175], v[222:225], v[68:71]
	v_mfma_f32_16x16x32_bf16 v[76:79], v[164:167], v[222:225], v[76:79]
	v_mfma_f32_16x16x32_bf16 v[76:79], v[160:163], v[218:221], v[76:79]
	s_setprio 0
	s_setprio 1
	v_mfma_f32_16x16x32_bf16 v[120:123], v[176:179], v[194:197], v[120:123]
	v_mfma_f32_16x16x32_bf16 v[120:123], v[180:183], v[198:201], v[120:123]
	v_mfma_f32_16x16x32_bf16 v[112:115], v[190:193], v[198:201], v[112:115]
	v_mfma_f32_16x16x32_bf16 v[112:115], v[186:189], v[194:197], v[112:115]
	v_mfma_f32_16x16x32_bf16 v[96:99], v[186:189], v[202:205], v[96:99]
	v_mfma_f32_16x16x32_bf16 v[96:99], v[190:193], v[206:209], v[96:99]
	v_mfma_f32_16x16x32_bf16 v[104:107], v[180:183], v[206:209], v[104:107]
	v_mfma_f32_16x16x32_bf16 v[104:107], v[176:179], v[202:205], v[104:107]
	v_mfma_f32_16x16x32_bf16 v[88:91], v[176:179], v[210:213], v[88:91]
	v_mfma_f32_16x16x32_bf16 v[88:91], v[180:183], v[214:217], v[88:91]
	v_mfma_f32_16x16x32_bf16 v[80:83], v[190:193], v[214:217], v[80:83]
	v_mfma_f32_16x16x32_bf16 v[80:83], v[186:189], v[210:213], v[80:83]
	v_mfma_f32_16x16x32_bf16 v[64:67], v[186:189], v[218:221], v[64:67]
	v_mfma_f32_16x16x32_bf16 v[64:67], v[190:193], v[222:225], v[64:67]
	v_mfma_f32_16x16x32_bf16 v[72:75], v[180:183], v[222:225], v[72:75]
	v_mfma_f32_16x16x32_bf16 v[72:75], v[176:179], v[218:221], v[72:75]
	s_setprio 0
	s_barrier
	s_add_i32 s48, s76, s52
	v_lshl_add_u64 v[154:155], v[154:155], 0, s[14:15]
	s_mov_b32 m0, s48
	ds_read_b128 v[194:197], v150 offset:49152
	v_xor_b32_e32 v253, 64, v150
	ds_read_b128 v[198:201], v253 offset:49152
	ds_read_b128 v[202:205], v150 offset:51200
	ds_read_b128 v[206:209], v253 offset:51200
	ds_read_b128 v[210:213], v150 offset:53248
	ds_read_b128 v[214:217], v253 offset:53248
	ds_read_b128 v[218:221], v150 offset:55296
	ds_read_b128 v[222:225], v253 offset:55296
	global_load_lds_dwordx4 v[154:155], off
	s_add_i32 m0, s48, 0x2000
	s_add_u32 s46, s46, 0x40080
	v_lshl_add_u64 v[154:155], v[226:227], 0, s[14:15]
	s_addc_u32 s47, s47, 0
	s_add_i32 s48, s77, s52
	global_load_lds_dwordx4 v[154:155], off
	v_lshl_add_u64 v[154:155], s[46:47], 0, v[132:133]
	s_mov_b32 m0, s48
	s_nop 0
	global_load_lds_dwordx4 v[154:155], off
	v_lshl_add_u64 v[154:155], s[46:47], 0, v[128:129]
	s_add_i32 m0, s48, 0x2000
	s_nop 0
	global_load_lds_dwordx4 v[154:155], off
	v_lshl_add_u64 v[154:155], v[228:229], 0, s[14:15]
	s_mov_b32 m0, s60
	s_nop 0
	global_load_lds_dwordx4 v[154:155], off
	v_lshl_add_u64 v[154:155], v[230:231], 0, s[14:15]
	s_mov_b32 m0, s61
	s_nop 0
	global_load_lds_dwordx4 v[154:155], off
	s_waitcnt vmcnt(8)
	s_waitcnt lgkmcnt(0)
	s_barrier
	s_setprio 1
	s_waitcnt lgkmcnt(0)
	v_mfma_f32_16x16x32_bf16 v[60:63], v[160:163], v[194:197], v[60:63]
	v_mfma_f32_16x16x32_bf16 v[60:63], v[164:167], v[198:201], v[60:63]
	v_mfma_f32_16x16x32_bf16 v[52:55], v[172:175], v[198:201], v[52:55]
	v_mfma_f32_16x16x32_bf16 v[52:55], v[168:171], v[194:197], v[52:55]
	v_mfma_f32_16x16x32_bf16 v[36:39], v[168:171], v[202:205], v[36:39]
	v_mfma_f32_16x16x32_bf16 v[36:39], v[172:175], v[206:209], v[36:39]
	v_mfma_f32_16x16x32_bf16 v[44:47], v[164:167], v[206:209], v[44:47]
	v_mfma_f32_16x16x32_bf16 v[44:47], v[160:163], v[202:205], v[44:47]
	v_mfma_f32_16x16x32_bf16 v[28:31], v[160:163], v[210:213], v[28:31]
	v_mfma_f32_16x16x32_bf16 v[28:31], v[164:167], v[214:217], v[28:31]
	v_mfma_f32_16x16x32_bf16 v[20:23], v[172:175], v[214:217], v[20:23]
	v_mfma_f32_16x16x32_bf16 v[20:23], v[168:171], v[210:213], v[20:23]
	v_mfma_f32_16x16x32_bf16 v[4:7], v[168:171], v[218:221], v[4:7]
	v_mfma_f32_16x16x32_bf16 v[4:7], v[172:175], v[222:225], v[4:7]
	v_mfma_f32_16x16x32_bf16 v[12:15], v[164:167], v[222:225], v[12:15]
	v_mfma_f32_16x16x32_bf16 v[12:15], v[160:163], v[218:221], v[12:15]
	s_setprio 0
	s_setprio 1
	v_mfma_f32_16x16x32_bf16 v[56:59], v[176:179], v[194:197], v[56:59]
	v_mfma_f32_16x16x32_bf16 v[56:59], v[180:183], v[198:201], v[56:59]
	v_mfma_f32_16x16x32_bf16 v[48:51], v[190:193], v[198:201], v[48:51]
	v_mfma_f32_16x16x32_bf16 v[48:51], v[186:189], v[194:197], v[48:51]
	v_mfma_f32_16x16x32_bf16 v[32:35], v[186:189], v[202:205], v[32:35]
	v_mfma_f32_16x16x32_bf16 v[32:35], v[190:193], v[206:209], v[32:35]
	v_mfma_f32_16x16x32_bf16 v[40:43], v[180:183], v[206:209], v[40:43]
	v_mfma_f32_16x16x32_bf16 v[40:43], v[176:179], v[202:205], v[40:43]
	v_mfma_f32_16x16x32_bf16 v[24:27], v[176:179], v[210:213], v[24:27]
	v_mfma_f32_16x16x32_bf16 v[24:27], v[180:183], v[214:217], v[24:27]
	v_mfma_f32_16x16x32_bf16 v[16:19], v[190:193], v[214:217], v[16:19]
	v_mfma_f32_16x16x32_bf16 v[16:19], v[186:189], v[210:213], v[16:19]
	v_mfma_f32_16x16x32_bf16 v[0:3], v[186:189], v[218:221], v[0:3]
	v_mfma_f32_16x16x32_bf16 v[0:3], v[190:193], v[222:225], v[0:3]
	v_mfma_f32_16x16x32_bf16 v[8:11], v[180:183], v[222:225], v[8:11]
	v_mfma_f32_16x16x32_bf16 v[8:11], v[176:179], v[218:221], v[8:11]
	s_setprio 0
	s_barrier
	s_add_i32 s75, s75, 2
	s_add_u32 s71, s71, 0x100
	s_addc_u32 s74, s74, 0
	s_add_u32 s44, s44, 0x100
	s_addc_u32 s45, s45, 0
	s_branch .LBB0_76

.LBB0_78:
	s_and_b64 vcc, exec, s[4:5]
	s_cbranch_vccnz .LBB0_80
	s_and_b64 vcc, exec, s[20:21]
	s_cbranch_vccz .LBB0_80
	s_barrier
.LBB0_80:
	s_andn2_b64 vcc, exec, s[4:5]
	s_cbranch_vccz .Lskip_e1_0
	v_add_u32_e32 v235, 0x84000, v235
	v_add_u32_e32 v234, 0x21800, v151
	ds_read_b128 v[236:239], v234
	ds_read_b128 v[240:243], v234 offset:256
	ds_read_b128 v[244:247], v234 offset:512
	ds_read_b128 v[248:251], v234 offset:768
	s_waitcnt lgkmcnt(0)
	v_add_f32_e32 v236, v236, v237
	v_add_f32_e32 v238, v238, v239
	v_add_f32_e32 v240, v240, v241
	v_add_f32_e32 v242, v242, v243
	v_add_f32_e32 v244, v244, v245
	v_add_f32_e32 v246, v246, v247
	v_add_f32_e32 v248, v248, v249
	v_add_f32_e32 v250, v250, v251
	v_add_f32_e32 v236, v236, v238
	v_add_f32_e32 v240, v240, v242
	v_add_f32_e32 v244, v244, v246
	v_add_f32_e32 v248, v248, v250
	v_fmamk_f32 v236, v236, 0x3a800000, v152
	v_fmamk_f32 v240, v240, 0x3a800000, v152
	v_fmamk_f32 v244, v244, 0x3a800000, v152
	v_fmamk_f32 v248, v248, 0x3a800000, v152
	v_rsq_f32_e32 v236, v236
	v_rsq_f32_e32 v240, v240
	v_rsq_f32_e32 v244, v244
	v_rsq_f32_e32 v248, v248
	v_mul_f32_e32 v252, 0xbfb8aa3b, v236
	v_mul_f32_e32 v254, v236, v236
	v_rcp_f32_e32 v254, v254
	v_pk_mul_f32 v[56:57], v[60:61], v[56:57]
	v_pk_mul_f32 v[58:59], v[62:63], v[58:59]
	v_pk_mul_f32 v[48:49], v[52:53], v[48:49]
	v_pk_mul_f32 v[50:51], v[54:55], v[50:51]
	v_pk_mul_f32 v[60:61], v[60:61], v[252:253] op_sel_hi:[1,0]
	v_pk_mul_f32 v[62:63], v[62:63], v[252:253] op_sel_hi:[1,0]
	v_pk_mul_f32 v[52:53], v[52:53], v[252:253] op_sel_hi:[1,0]
	v_pk_mul_f32 v[54:55], v[54:55], v[252:253] op_sel_hi:[1,0]
	v_exp_f32_e32 v60, v60
	v_exp_f32_e32 v61, v61
	v_exp_f32_e32 v62, v62
	v_exp_f32_e32 v63, v63
	v_exp_f32_e32 v52, v52
	v_exp_f32_e32 v53, v53
	v_exp_f32_e32 v54, v54
	v_exp_f32_e32 v55, v55
	v_pk_fma_f32 v[60:61], v[60:61], v[254:255], v[254:255] op_sel_hi:[1,0,0]
	v_pk_fma_f32 v[62:63], v[62:63], v[254:255], v[254:255] op_sel_hi:[1,0,0]
	v_pk_fma_f32 v[52:53], v[52:53], v[254:255], v[254:255] op_sel_hi:[1,0,0]
	v_pk_fma_f32 v[54:55], v[54:55], v[254:255], v[254:255] op_sel_hi:[1,0,0]
	v_rcp_f32_e32 v60, v60
	v_rcp_f32_e32 v61, v61
	v_rcp_f32_e32 v62, v62
	v_rcp_f32_e32 v63, v63
	v_rcp_f32_e32 v52, v52
	v_rcp_f32_e32 v53, v53
	v_rcp_f32_e32 v54, v54
	v_rcp_f32_e32 v55, v55
	v_pk_mul_f32 v[56:57], v[56:57], v[60:61]
	v_pk_mul_f32 v[58:59], v[58:59], v[62:63]
	v_pk_mul_f32 v[48:49], v[48:49], v[52:53]
	v_pk_mul_f32 v[50:51], v[50:51], v[54:55]
	v_cvt_pk_bf16_f32 v56, v56, v57
	v_cvt_pk_bf16_f32 v57, v58, v59
	v_cvt_pk_bf16_f32 v58, v48, v49
	v_cvt_pk_bf16_f32 v59, v50, v51
	global_store_dwordx4 v235, v[56:59], s[10:11]
	v_add_u32_e32 v234, 0x16000, v235
	v_mul_f32_e32 v252, 0xbfb8aa3b, v240
	v_mul_f32_e32 v254, v240, v240
	v_rcp_f32_e32 v254, v254
	v_pk_mul_f32 v[40:41], v[44:45], v[40:41]
	v_pk_mul_f32 v[42:43], v[46:47], v[42:43]
	v_pk_mul_f32 v[32:33], v[36:37], v[32:33]
	v_pk_mul_f32 v[34:35], v[38:39], v[34:35]
	v_pk_mul_f32 v[44:45], v[44:45], v[252:253] op_sel_hi:[1,0]
	v_pk_mul_f32 v[46:47], v[46:47], v[252:253] op_sel_hi:[1,0]
	v_pk_mul_f32 v[36:37], v[36:37], v[252:253] op_sel_hi:[1,0]
	v_pk_mul_f32 v[38:39], v[38:39], v[252:253] op_sel_hi:[1,0]
	v_exp_f32_e32 v44, v44
	v_exp_f32_e32 v45, v45
	v_exp_f32_e32 v46, v46
	v_exp_f32_e32 v47, v47
	v_exp_f32_e32 v36, v36
	v_exp_f32_e32 v37, v37
	v_exp_f32_e32 v38, v38
	v_exp_f32_e32 v39, v39
	v_pk_fma_f32 v[44:45], v[44:45], v[254:255], v[254:255] op_sel_hi:[1,0,0]
	v_pk_fma_f32 v[46:47], v[46:47], v[254:255], v[254:255] op_sel_hi:[1,0,0]
	v_pk_fma_f32 v[36:37], v[36:37], v[254:255], v[254:255] op_sel_hi:[1,0,0]
	v_pk_fma_f32 v[38:39], v[38:39], v[254:255], v[254:255] op_sel_hi:[1,0,0]
	v_rcp_f32_e32 v44, v44
	v_rcp_f32_e32 v45, v45
	v_rcp_f32_e32 v46, v46
	v_rcp_f32_e32 v47, v47
	v_rcp_f32_e32 v36, v36
	v_rcp_f32_e32 v37, v37
	v_rcp_f32_e32 v38, v38
	v_rcp_f32_e32 v39, v39
	v_pk_mul_f32 v[40:41], v[40:41], v[44:45]
	v_pk_mul_f32 v[42:43], v[42:43], v[46:47]
	v_pk_mul_f32 v[32:33], v[32:33], v[36:37]
	v_pk_mul_f32 v[34:35], v[34:35], v[38:39]
	v_cvt_pk_bf16_f32 v40, v40, v41
	v_cvt_pk_bf16_f32 v41, v42, v43
	v_cvt_pk_bf16_f32 v42, v32, v33
	v_cvt_pk_bf16_f32 v43, v34, v35
	global_store_dwordx4 v234, v[40:43], s[10:11]
	v_add_u32_e32 v235, 0x16000, v234
	v_mul_f32_e32 v252, 0xbfb8aa3b, v244
	v_mul_f32_e32 v254, v244, v244
	v_rcp_f32_e32 v254, v254
	v_pk_mul_f32 v[24:25], v[28:29], v[24:25]
	v_pk_mul_f32 v[26:27], v[30:31], v[26:27]
	v_pk_mul_f32 v[16:17], v[20:21], v[16:17]
	v_pk_mul_f32 v[18:19], v[22:23], v[18:19]
	v_pk_mul_f32 v[28:29], v[28:29], v[252:253] op_sel_hi:[1,0]
	v_pk_mul_f32 v[30:31], v[30:31], v[252:253] op_sel_hi:[1,0]
	v_pk_mul_f32 v[20:21], v[20:21], v[252:253] op_sel_hi:[1,0]
	v_pk_mul_f32 v[22:23], v[22:23], v[252:253] op_sel_hi:[1,0]
	v_exp_f32_e32 v28, v28
	v_exp_f32_e32 v29, v29
	v_exp_f32_e32 v30, v30
	v_exp_f32_e32 v31, v31
	v_exp_f32_e32 v20, v20
	v_exp_f32_e32 v21, v21
	v_exp_f32_e32 v22, v22
	v_exp_f32_e32 v23, v23
	v_pk_fma_f32 v[28:29], v[28:29], v[254:255], v[254:255] op_sel_hi:[1,0,0]
	v_pk_fma_f32 v[30:31], v[30:31], v[254:255], v[254:255] op_sel_hi:[1,0,0]
	v_pk_fma_f32 v[20:21], v[20:21], v[254:255], v[254:255] op_sel_hi:[1,0,0]
	v_pk_fma_f32 v[22:23], v[22:23], v[254:255], v[254:255] op_sel_hi:[1,0,0]
	v_rcp_f32_e32 v28, v28
	v_rcp_f32_e32 v29, v29
	v_rcp_f32_e32 v30, v30
	v_rcp_f32_e32 v31, v31
	v_rcp_f32_e32 v20, v20
	v_rcp_f32_e32 v21, v21
	v_rcp_f32_e32 v22, v22
	v_rcp_f32_e32 v23, v23
	v_pk_mul_f32 v[24:25], v[24:25], v[28:29]
	v_pk_mul_f32 v[26:27], v[26:27], v[30:31]
	v_pk_mul_f32 v[16:17], v[16:17], v[20:21]
	v_pk_mul_f32 v[18:19], v[18:19], v[22:23]
	v_cvt_pk_bf16_f32 v24, v24, v25
	v_cvt_pk_bf16_f32 v25, v26, v27
	v_cvt_pk_bf16_f32 v26, v16, v17
	v_cvt_pk_bf16_f32 v27, v18, v19
	global_store_dwordx4 v235, v[24:27], s[10:11]
	v_add_u32_e32 v234, 0x16000, v235
	v_mul_f32_e32 v252, 0xbfb8aa3b, v248
	v_mul_f32_e32 v254, v248, v248
	v_rcp_f32_e32 v254, v254
	v_pk_mul_f32 v[8:9], v[12:13], v[8:9]
	v_pk_mul_f32 v[10:11], v[14:15], v[10:11]
	v_pk_mul_f32 v[0:1], v[4:5], v[0:1]
	v_pk_mul_f32 v[2:3], v[6:7], v[2:3]
	v_pk_mul_f32 v[12:13], v[12:13], v[252:253] op_sel_hi:[1,0]
	v_pk_mul_f32 v[14:15], v[14:15], v[252:253] op_sel_hi:[1,0]
	v_pk_mul_f32 v[4:5], v[4:5], v[252:253] op_sel_hi:[1,0]
	v_pk_mul_f32 v[6:7], v[6:7], v[252:253] op_sel_hi:[1,0]
	v_exp_f32_e32 v12, v12
	v_exp_f32_e32 v13, v13
	v_exp_f32_e32 v14, v14
	v_exp_f32_e32 v15, v15
	v_exp_f32_e32 v4, v4
	v_exp_f32_e32 v5, v5
	v_exp_f32_e32 v6, v6
	v_exp_f32_e32 v7, v7
	v_pk_fma_f32 v[12:13], v[12:13], v[254:255], v[254:255] op_sel_hi:[1,0,0]
	v_pk_fma_f32 v[14:15], v[14:15], v[254:255], v[254:255] op_sel_hi:[1,0,0]
	v_pk_fma_f32 v[4:5], v[4:5], v[254:255], v[254:255] op_sel_hi:[1,0,0]
	v_pk_fma_f32 v[6:7], v[6:7], v[254:255], v[254:255] op_sel_hi:[1,0,0]
	v_rcp_f32_e32 v12, v12
	v_rcp_f32_e32 v13, v13
	v_rcp_f32_e32 v14, v14
	v_rcp_f32_e32 v15, v15
	v_rcp_f32_e32 v4, v4
	v_rcp_f32_e32 v5, v5
	v_rcp_f32_e32 v6, v6
	v_rcp_f32_e32 v7, v7
	v_pk_mul_f32 v[8:9], v[8:9], v[12:13]
	v_pk_mul_f32 v[10:11], v[10:11], v[14:15]
	v_pk_mul_f32 v[0:1], v[0:1], v[4:5]
	v_pk_mul_f32 v[2:3], v[2:3], v[6:7]
	v_cvt_pk_bf16_f32 v8, v8, v9
	v_cvt_pk_bf16_f32 v9, v10, v11
	v_cvt_pk_bf16_f32 v10, v0, v1
	v_cvt_pk_bf16_f32 v11, v2, v3
	global_store_dwordx4 v234, v[8:11], s[10:11]
.Lskip_e1_0:
	s_mov_b64 s[4:5], -1
	s_cbranch_vccnz .LBB0_71
	s_andn2_b64 vcc, exec, s[8:9]
	s_cbranch_vccnz .LBB0_70
	s_branch .LBB0_70

.Lwgm_orig_2:
	s_ashr_i32 s26, s30, 31
	s_lshr_b32 s26, s26, 29
	s_add_i32 s26, s30, s26
	s_ashr_i32 s27, s26, 3
	s_and_b32 s26, s26, -8
	s_sub_i32 s26, s30, s26
	s_cmp_lt_i32 s26, 0
	s_cselect_b32 s28, s56, 0x160
	s_mul_i32 s26, s28, s26
	s_add_i32 s26, s26, s27
	s_mul_hi_i32 s27, s26, 0x2e8ba2e9
	s_lshr_b32 s28, s27, 31
	s_ashr_i32 s27, s27, 3
	s_add_i32 s27, s27, s28
	s_lshl_b32 s28, s27, 1
	s_sub_i32 s29, 0x80, s28
	s_min_i32 s29, s29, 2
	s_abs_i32 s30, s29
	v_cvt_f32_u32_e32 v250, s30
	s_sub_i32 s44, 0, s30
	s_mul_i32 s27, s27, 44
	s_sub_i32 s27, s26, s27
	v_rcp_iflag_f32_e32 v250, v250
	s_abs_i32 s26, s27
	s_xor_b32 s31, s27, s29
	s_ashr_i32 s31, s31, 31
	v_mul_f32_e32 v250, 0x4f7ffffe, v250
	v_cvt_u32_f32_e32 v250, v250
	s_nop 0
	v_readfirstlane_b32 s45, v250
	s_mul_i32 s44, s44, s45
	s_mul_hi_u32 s44, s45, s44
	s_add_i32 s45, s45, s44
	s_mul_hi_u32 s44, s26, s45
	s_mul_i32 s45, s44, s30
	s_sub_i32 s26, s26, s45
	s_add_i32 s47, s44, 1
	s_sub_i32 s45, s26, s30
	s_cmp_ge_u32 s26, s30
	s_cselect_b32 s44, s47, s44
	s_cselect_b32 s26, s45, s26
	s_add_i32 s45, s44, 1
	s_cmp_ge_u32 s26, s30
	s_cselect_b32 s26, s45, s44
	s_xor_b32 s26, s26, s31
	s_sub_i32 s26, s26, s31
	s_mul_i32 s29, s26, s29
	s_sub_i32 s27, s27, s29
	s_add_i32 s28, s27, s28
.LBB0_525:
	s_ashr_i32 s29, s28, 31
	s_lshl_b64 s[30:31], s[28:29], 19
	s_add_u32 s30, s3, s30
	s_addc_u32 s31, s35, s31
	s_and_b64 s[44:45], s[10:11], exec
	s_cselect_b32 s29, s31, s51
	s_cselect_b32 s70, s30, s50
	s_ashr_i32 s27, s26, 31
	s_lshl_b64 s[44:45], s[26:27], 19
	s_add_u32 s44, s52, s44
	s_addc_u32 s45, s53, s45
	s_and_b64 s[72:73], s[10:11], exec
	s_cselect_b32 s71, s45, s49
	s_cselect_b32 s72, s44, s48
	s_lshl_b32 s27, s46, 8
	v_add_u32_e32 v250, s27, v148
	s_add_u32 s73, s48, 0x100
	v_ashrrev_i32_e32 v251, 31, v250
	s_addc_u32 s74, s49, 0
	v_lshl_add_u64 v[144:145], v[250:251], 4, s[16:17]
	s_add_u32 s46, s50, 0x40080
	s_addc_u32 s47, s51, 0
	s_mov_b32 s75, -2
	s_mov_b64 s[48:49], 0
	s_cmp_eq_u32 s61, 1
	s_cbranch_scc1 .Lfa_4
	v_add_u32_e32 v153, s66, v147
	ds_read_b128 v[160:163], v153
	v_xor_b32_e32 v253, 64, v153
	ds_read_b128 v[164:167], v253
	ds_read_b128 v[168:171], v153 offset:2048
	ds_read_b128 v[172:175], v253 offset:2048
	v_add_u32_e32 v153, s67, v147
	ds_read_b128 v[176:179], v153
	v_xor_b32_e32 v253, 64, v153
	ds_read_b128 v[180:183], v253
	ds_read_b128 v[186:189], v153 offset:2048
	ds_read_b128 v[190:193], v253 offset:2048
	s_add_u32 s50, s46, 0xfffc0080
	s_addc_u32 s51, s47, -1
	s_and_b64 s[48:49], s[48:49], exec
	s_cselect_b32 s51, s29, s51
	s_cselect_b32 s50, s70, s50
	s_cselect_b32 s49, s71, s74
	s_cselect_b32 s48, s72, s73
	v_lshl_add_u64 v[154:155], s[46:47], 0, v[138:139]
	s_add_i32 m0, s57, 0xc000
	ds_read_b128 v[194:197], v150
	v_xor_b32_e32 v253, 64, v150
	ds_read_b128 v[198:201], v253
	ds_read_b128 v[202:205], v150 offset:2048
	ds_read_b128 v[206:209], v253 offset:2048
	ds_read_b128 v[210:213], v150 offset:4096
	ds_read_b128 v[214:217], v253 offset:4096
	ds_read_b128 v[218:221], v150 offset:6144
	ds_read_b128 v[222:225], v253 offset:6144
	global_load_lds_dwordx4 v[154:155], off
	v_lshl_add_u64 v[154:155], s[46:47], 0, v[136:137]
	s_add_i32 m0, s57, 0xe000
	s_nop 0
	global_load_lds_dwordx4 v[154:155], off
	s_waitcnt lgkmcnt(0)
	v_add_u32_e32 v235, 0x84000, v235
	v_add_u32_e32 v234, 0x21800, v151
	ds_read_b128 v[236:239], v234
	ds_read_b128 v[240:243], v234 offset:256
	ds_read_b128 v[244:247], v234 offset:512
	ds_read_b128 v[248:251], v234 offset:768
	s_waitcnt lgkmcnt(0)
	v_add_f32_e32 v236, v236, v237
	v_add_f32_e32 v238, v238, v239
	v_add_f32_e32 v240, v240, v241
	v_add_f32_e32 v242, v242, v243
	v_add_f32_e32 v244, v244, v245
	v_add_f32_e32 v246, v246, v247
	v_add_f32_e32 v248, v248, v249
	v_add_f32_e32 v250, v250, v251
	v_add_f32_e32 v236, v236, v238
	v_add_f32_e32 v240, v240, v242
	v_add_f32_e32 v244, v244, v246
	v_add_f32_e32 v248, v248, v250
	v_fmamk_f32 v236, v236, 0x3a800000, v152
	v_fmamk_f32 v240, v240, 0x3a800000, v152
	v_fmamk_f32 v244, v244, 0x3a800000, v152
	v_fmamk_f32 v248, v248, 0x3a800000, v152
	v_rsq_f32_e32 v236, v236
	v_rsq_f32_e32 v240, v240
	v_rsq_f32_e32 v244, v244
	v_rsq_f32_e32 v248, v248
	v_mul_f32_e32 v252, 0xbfb8aa3b, v236
	v_mul_f32_e32 v254, v236, v236
	v_rcp_f32_e32 v254, v254
	v_pk_mul_f32 v[56:57], v[60:61], v[56:57]
	v_pk_mul_f32 v[58:59], v[62:63], v[58:59]
	v_pk_mul_f32 v[48:49], v[52:53], v[48:49]
	v_pk_mul_f32 v[50:51], v[54:55], v[50:51]
	v_pk_mul_f32 v[60:61], v[60:61], v[252:253] op_sel_hi:[1,0]
	v_pk_mul_f32 v[62:63], v[62:63], v[252:253] op_sel_hi:[1,0]
	v_pk_mul_f32 v[52:53], v[52:53], v[252:253] op_sel_hi:[1,0]
	v_pk_mul_f32 v[54:55], v[54:55], v[252:253] op_sel_hi:[1,0]
	v_exp_f32_e32 v60, v60
	v_exp_f32_e32 v61, v61
	v_exp_f32_e32 v62, v62
	v_exp_f32_e32 v63, v63
	v_exp_f32_e32 v52, v52
	v_exp_f32_e32 v53, v53
	v_exp_f32_e32 v54, v54
	v_exp_f32_e32 v55, v55
	v_pk_fma_f32 v[60:61], v[60:61], v[254:255], v[254:255] op_sel_hi:[1,0,0]
	v_pk_fma_f32 v[62:63], v[62:63], v[254:255], v[254:255] op_sel_hi:[1,0,0]
	v_pk_fma_f32 v[52:53], v[52:53], v[254:255], v[254:255] op_sel_hi:[1,0,0]
	v_pk_fma_f32 v[54:55], v[54:55], v[254:255], v[254:255] op_sel_hi:[1,0,0]
	v_rcp_f32_e32 v60, v60
	v_rcp_f32_e32 v61, v61
	v_rcp_f32_e32 v62, v62
	v_rcp_f32_e32 v63, v63
	v_rcp_f32_e32 v52, v52
	v_rcp_f32_e32 v53, v53
	v_rcp_f32_e32 v54, v54
	v_rcp_f32_e32 v55, v55
	v_pk_mul_f32 v[56:57], v[56:57], v[60:61]
	v_pk_mul_f32 v[58:59], v[58:59], v[62:63]
	v_pk_mul_f32 v[48:49], v[48:49], v[52:53]
	v_pk_mul_f32 v[50:51], v[50:51], v[54:55]
	v_cvt_pk_bf16_f32 v56, v56, v57
	v_cvt_pk_bf16_f32 v57, v58, v59
	v_cvt_pk_bf16_f32 v58, v48, v49
	v_cvt_pk_bf16_f32 v59, v50, v51
	global_store_dwordx4 v235, v[56:59], s[14:15]
	v_add_u32_e32 v234, 0x16000, v235
	v_mul_f32_e32 v252, 0xbfb8aa3b, v240
	v_mul_f32_e32 v254, v240, v240
	v_rcp_f32_e32 v254, v254
	v_pk_mul_f32 v[40:41], v[44:45], v[40:41]
	v_pk_mul_f32 v[42:43], v[46:47], v[42:43]
	v_pk_mul_f32 v[32:33], v[36:37], v[32:33]
	v_pk_mul_f32 v[34:35], v[38:39], v[34:35]
	v_pk_mul_f32 v[44:45], v[44:45], v[252:253] op_sel_hi:[1,0]
	v_pk_mul_f32 v[46:47], v[46:47], v[252:253] op_sel_hi:[1,0]
	v_pk_mul_f32 v[36:37], v[36:37], v[252:253] op_sel_hi:[1,0]
	v_pk_mul_f32 v[38:39], v[38:39], v[252:253] op_sel_hi:[1,0]
	v_exp_f32_e32 v44, v44
	v_exp_f32_e32 v45, v45
	v_exp_f32_e32 v46, v46
	v_exp_f32_e32 v47, v47
	v_exp_f32_e32 v36, v36
	v_exp_f32_e32 v37, v37
	v_exp_f32_e32 v38, v38
	v_exp_f32_e32 v39, v39
	v_pk_fma_f32 v[44:45], v[44:45], v[254:255], v[254:255] op_sel_hi:[1,0,0]
	v_pk_fma_f32 v[46:47], v[46:47], v[254:255], v[254:255] op_sel_hi:[1,0,0]
	v_pk_fma_f32 v[36:37], v[36:37], v[254:255], v[254:255] op_sel_hi:[1,0,0]
	v_pk_fma_f32 v[38:39], v[38:39], v[254:255], v[254:255] op_sel_hi:[1,0,0]
	v_rcp_f32_e32 v44, v44
	v_rcp_f32_e32 v45, v45
	v_rcp_f32_e32 v46, v46
	v_rcp_f32_e32 v47, v47
	v_rcp_f32_e32 v36, v36
	v_rcp_f32_e32 v37, v37
	v_rcp_f32_e32 v38, v38
	v_rcp_f32_e32 v39, v39
	v_pk_mul_f32 v[40:41], v[40:41], v[44:45]
	v_pk_mul_f32 v[42:43], v[42:43], v[46:47]
	v_pk_mul_f32 v[32:33], v[32:33], v[36:37]
	v_pk_mul_f32 v[34:35], v[34:35], v[38:39]
	v_cvt_pk_bf16_f32 v40, v40, v41
	v_cvt_pk_bf16_f32 v41, v42, v43
	v_cvt_pk_bf16_f32 v42, v32, v33
	v_cvt_pk_bf16_f32 v43, v34, v35
	global_store_dwordx4 v234, v[40:43], s[14:15]
	v_add_u32_e32 v235, 0x16000, v234
	v_mul_f32_e32 v252, 0xbfb8aa3b, v244
	v_mul_f32_e32 v254, v244, v244
	v_rcp_f32_e32 v254, v254
	v_pk_mul_f32 v[24:25], v[28:29], v[24:25]
	v_pk_mul_f32 v[26:27], v[30:31], v[26:27]
	v_pk_mul_f32 v[16:17], v[20:21], v[16:17]
	v_pk_mul_f32 v[18:19], v[22:23], v[18:19]
	v_pk_mul_f32 v[28:29], v[28:29], v[252:253] op_sel_hi:[1,0]
	v_pk_mul_f32 v[30:31], v[30:31], v[252:253] op_sel_hi:[1,0]
	v_pk_mul_f32 v[20:21], v[20:21], v[252:253] op_sel_hi:[1,0]
	v_pk_mul_f32 v[22:23], v[22:23], v[252:253] op_sel_hi:[1,0]
	v_exp_f32_e32 v28, v28
	v_exp_f32_e32 v29, v29
	v_exp_f32_e32 v30, v30
	v_exp_f32_e32 v31, v31
	v_exp_f32_e32 v20, v20
	v_exp_f32_e32 v21, v21
	v_exp_f32_e32 v22, v22
	v_exp_f32_e32 v23, v23
	v_pk_fma_f32 v[28:29], v[28:29], v[254:255], v[254:255] op_sel_hi:[1,0,0]
	v_pk_fma_f32 v[30:31], v[30:31], v[254:255], v[254:255] op_sel_hi:[1,0,0]
	v_pk_fma_f32 v[20:21], v[20:21], v[254:255], v[254:255] op_sel_hi:[1,0,0]
	v_pk_fma_f32 v[22:23], v[22:23], v[254:255], v[254:255] op_sel_hi:[1,0,0]
	v_rcp_f32_e32 v28, v28
	v_rcp_f32_e32 v29, v29
	v_rcp_f32_e32 v30, v30
	v_rcp_f32_e32 v31, v31
	v_rcp_f32_e32 v20, v20
	v_rcp_f32_e32 v21, v21
	v_rcp_f32_e32 v22, v22
	v_rcp_f32_e32 v23, v23
	v_pk_mul_f32 v[24:25], v[24:25], v[28:29]
	v_pk_mul_f32 v[26:27], v[26:27], v[30:31]
	v_pk_mul_f32 v[16:17], v[16:17], v[20:21]
	v_pk_mul_f32 v[18:19], v[18:19], v[22:23]
	v_cvt_pk_bf16_f32 v24, v24, v25
	v_cvt_pk_bf16_f32 v25, v26, v27
	v_cvt_pk_bf16_f32 v26, v16, v17
	v_cvt_pk_bf16_f32 v27, v18, v19
	global_store_dwordx4 v235, v[24:27], s[14:15]
	v_add_u32_e32 v234, 0x16000, v235
	v_mul_f32_e32 v252, 0xbfb8aa3b, v248
	v_mul_f32_e32 v254, v248, v248
	v_rcp_f32_e32 v254, v254
	v_pk_mul_f32 v[8:9], v[12:13], v[8:9]
	v_pk_mul_f32 v[10:11], v[14:15], v[10:11]
	v_pk_mul_f32 v[0:1], v[4:5], v[0:1]
	v_pk_mul_f32 v[2:3], v[6:7], v[2:3]
	v_pk_mul_f32 v[12:13], v[12:13], v[252:253] op_sel_hi:[1,0]
	v_pk_mul_f32 v[14:15], v[14:15], v[252:253] op_sel_hi:[1,0]
	v_pk_mul_f32 v[4:5], v[4:5], v[252:253] op_sel_hi:[1,0]
	v_pk_mul_f32 v[6:7], v[6:7], v[252:253] op_sel_hi:[1,0]
	v_exp_f32_e32 v12, v12
	v_exp_f32_e32 v13, v13
	v_exp_f32_e32 v14, v14
	v_exp_f32_e32 v15, v15
	v_exp_f32_e32 v4, v4
	v_exp_f32_e32 v5, v5
	v_exp_f32_e32 v6, v6
	v_exp_f32_e32 v7, v7
	v_pk_fma_f32 v[12:13], v[12:13], v[254:255], v[254:255] op_sel_hi:[1,0,0]
	v_pk_fma_f32 v[14:15], v[14:15], v[254:255], v[254:255] op_sel_hi:[1,0,0]
	v_pk_fma_f32 v[4:5], v[4:5], v[254:255], v[254:255] op_sel_hi:[1,0,0]
	v_pk_fma_f32 v[6:7], v[6:7], v[254:255], v[254:255] op_sel_hi:[1,0,0]
	v_rcp_f32_e32 v12, v12
	v_rcp_f32_e32 v13, v13
	v_rcp_f32_e32 v14, v14
	v_rcp_f32_e32 v15, v15
	v_rcp_f32_e32 v4, v4
	v_rcp_f32_e32 v5, v5
	v_rcp_f32_e32 v6, v6
	v_rcp_f32_e32 v7, v7
	v_pk_mul_f32 v[8:9], v[8:9], v[12:13]
	v_pk_mul_f32 v[10:11], v[10:11], v[14:15]
	v_pk_mul_f32 v[0:1], v[0:1], v[4:5]
	v_pk_mul_f32 v[2:3], v[2:3], v[6:7]
	v_cvt_pk_bf16_f32 v8, v8, v9
	v_cvt_pk_bf16_f32 v9, v10, v11
	v_cvt_pk_bf16_f32 v10, v0, v1
	v_cvt_pk_bf16_f32 v11, v2, v3
	global_store_dwordx4 v234, v[8:11], s[14:15]
	s_waitcnt vmcnt(16)
	s_waitcnt lgkmcnt(0)
	s_barrier
	s_setprio 1
	s_waitcnt lgkmcnt(0)
	v_mfma_f32_16x16x32_bf16 v[124:127], v[160:163], v[194:197], 0
	v_mfma_f32_16x16x32_bf16 v[116:119], v[168:171], v[194:197], 0
	v_mfma_f32_16x16x32_bf16 v[108:111], v[160:163], v[202:205], 0
	v_mfma_f32_16x16x32_bf16 v[100:103], v[168:171], v[202:205], 0
	v_mfma_f32_16x16x32_bf16 v[92:95], v[160:163], v[210:213], 0
	v_mfma_f32_16x16x32_bf16 v[84:87], v[168:171], v[210:213], 0
	v_mfma_f32_16x16x32_bf16 v[76:79], v[160:163], v[218:221], 0
	v_mfma_f32_16x16x32_bf16 v[68:71], v[168:171], v[218:221], 0
	v_mfma_f32_16x16x32_bf16 v[124:127], v[164:167], v[198:201], v[124:127]
	v_mfma_f32_16x16x32_bf16 v[116:119], v[172:175], v[198:201], v[116:119]
	v_mfma_f32_16x16x32_bf16 v[108:111], v[164:167], v[206:209], v[108:111]
	v_mfma_f32_16x16x32_bf16 v[100:103], v[172:175], v[206:209], v[100:103]
	v_mfma_f32_16x16x32_bf16 v[92:95], v[164:167], v[214:217], v[92:95]
	v_mfma_f32_16x16x32_bf16 v[84:87], v[172:175], v[214:217], v[84:87]
	v_mfma_f32_16x16x32_bf16 v[76:79], v[164:167], v[222:225], v[76:79]
	v_mfma_f32_16x16x32_bf16 v[68:71], v[172:175], v[222:225], v[68:71]
	s_setprio 0
	s_setprio 1
	v_mfma_f32_16x16x32_bf16 v[120:123], v[176:179], v[194:197], 0
	v_mfma_f32_16x16x32_bf16 v[112:115], v[186:189], v[194:197], 0
	v_mfma_f32_16x16x32_bf16 v[104:107], v[176:179], v[202:205], 0
	v_mfma_f32_16x16x32_bf16 v[96:99], v[186:189], v[202:205], 0
	v_mfma_f32_16x16x32_bf16 v[88:91], v[176:179], v[210:213], 0
	v_mfma_f32_16x16x32_bf16 v[80:83], v[186:189], v[210:213], 0
	v_mfma_f32_16x16x32_bf16 v[72:75], v[176:179], v[218:221], 0
	v_mfma_f32_16x16x32_bf16 v[64:67], v[186:189], v[218:221], 0
	v_mfma_f32_16x16x32_bf16 v[120:123], v[180:183], v[198:201], v[120:123]
	v_mfma_f32_16x16x32_bf16 v[112:115], v[190:193], v[198:201], v[112:115]
	v_mfma_f32_16x16x32_bf16 v[104:107], v[180:183], v[206:209], v[104:107]
	v_mfma_f32_16x16x32_bf16 v[96:99], v[190:193], v[206:209], v[96:99]
	v_mfma_f32_16x16x32_bf16 v[88:91], v[180:183], v[214:217], v[88:91]
	v_mfma_f32_16x16x32_bf16 v[80:83], v[190:193], v[214:217], v[80:83]
	v_mfma_f32_16x16x32_bf16 v[72:75], v[180:183], v[222:225], v[72:75]
	v_mfma_f32_16x16x32_bf16 v[64:67], v[190:193], v[222:225], v[64:67]
	s_setprio 0
	s_barrier
	s_add_i32 s76, s66, s54
	v_lshl_add_u64 v[154:155], s[48:49], 0, v[132:133]
	s_mov_b32 m0, s76
	ds_read_b128 v[194:197], v150 offset:16384
	v_xor_b32_e32 v253, 64, v150
	ds_read_b128 v[198:201], v253 offset:16384
	ds_read_b128 v[202:205], v150 offset:18432
	ds_read_b128 v[206:209], v253 offset:18432
	ds_read_b128 v[210:213], v150 offset:20480
	ds_read_b128 v[214:217], v253 offset:20480
	ds_read_b128 v[218:221], v150 offset:22528
	ds_read_b128 v[222:225], v253 offset:22528
	global_load_lds_dwordx4 v[154:155], off
	s_add_i32 m0, s76, 0x2000
	s_add_u32 s76, s48, 0x40000
	v_lshl_add_u64 v[226:227], s[48:49], 0, v[128:129]
	s_addc_u32 s77, s49, 0
	s_add_i32 s78, s67, s54
	global_load_lds_dwordx4 v[226:227], off
	v_lshl_add_u64 v[228:229], s[76:77], 0, v[132:133]
	s_mov_b32 m0, s78
	v_lshl_add_u64 v[230:231], s[50:51], 0, v[130:131]
	global_load_lds_dwordx4 v[228:229], off
	v_lshl_add_u64 v[228:229], s[76:77], 0, v[128:129]
	s_add_i32 m0, s78, 0x2000
	s_nop 0
	global_load_lds_dwordx4 v[228:229], off
	v_lshl_add_u64 v[228:229], s[50:51], 0, v[134:135]
	s_mov_b32 m0, s57
	s_nop 0
	global_load_lds_dwordx4 v[228:229], off
	s_mov_b32 m0, s58
	s_nop 0
	global_load_lds_dwordx4 v[230:231], off
	s_waitcnt vmcnt(16)
	s_waitcnt lgkmcnt(0)
	s_barrier
	s_setprio 1
	s_waitcnt lgkmcnt(0)
	v_mfma_f32_16x16x32_bf16 v[60:63], v[160:163], v[194:197], 0
	v_mfma_f32_16x16x32_bf16 v[52:55], v[168:171], v[194:197], 0
	v_mfma_f32_16x16x32_bf16 v[44:47], v[160:163], v[202:205], 0
	v_mfma_f32_16x16x32_bf16 v[36:39], v[168:171], v[202:205], 0
	v_mfma_f32_16x16x32_bf16 v[28:31], v[160:163], v[210:213], 0
	v_mfma_f32_16x16x32_bf16 v[20:23], v[168:171], v[210:213], 0
	v_mfma_f32_16x16x32_bf16 v[12:15], v[160:163], v[218:221], 0
	v_mfma_f32_16x16x32_bf16 v[4:7], v[168:171], v[218:221], 0
	v_mfma_f32_16x16x32_bf16 v[60:63], v[164:167], v[198:201], v[60:63]
	v_mfma_f32_16x16x32_bf16 v[52:55], v[172:175], v[198:201], v[52:55]
	v_mfma_f32_16x16x32_bf16 v[44:47], v[164:167], v[206:209], v[44:47]
	v_mfma_f32_16x16x32_bf16 v[36:39], v[172:175], v[206:209], v[36:39]
	v_mfma_f32_16x16x32_bf16 v[28:31], v[164:167], v[214:217], v[28:31]
	v_mfma_f32_16x16x32_bf16 v[20:23], v[172:175], v[214:217], v[20:23]
	v_mfma_f32_16x16x32_bf16 v[12:15], v[164:167], v[222:225], v[12:15]
	v_mfma_f32_16x16x32_bf16 v[4:7], v[172:175], v[222:225], v[4:7]
	s_setprio 0
	s_setprio 1
	v_mfma_f32_16x16x32_bf16 v[56:59], v[176:179], v[194:197], 0
	v_mfma_f32_16x16x32_bf16 v[48:51], v[186:189], v[194:197], 0
	v_mfma_f32_16x16x32_bf16 v[40:43], v[176:179], v[202:205], 0
	v_mfma_f32_16x16x32_bf16 v[32:35], v[186:189], v[202:205], 0
	v_mfma_f32_16x16x32_bf16 v[24:27], v[176:179], v[210:213], 0
	v_mfma_f32_16x16x32_bf16 v[16:19], v[186:189], v[210:213], 0
	v_mfma_f32_16x16x32_bf16 v[8:11], v[176:179], v[218:221], 0
	v_mfma_f32_16x16x32_bf16 v[0:3], v[186:189], v[218:221], 0
	v_mfma_f32_16x16x32_bf16 v[56:59], v[180:183], v[198:201], v[56:59]
	v_mfma_f32_16x16x32_bf16 v[48:51], v[190:193], v[198:201], v[48:51]
	v_mfma_f32_16x16x32_bf16 v[40:43], v[180:183], v[206:209], v[40:43]
	v_mfma_f32_16x16x32_bf16 v[32:35], v[190:193], v[206:209], v[32:35]
	v_mfma_f32_16x16x32_bf16 v[24:27], v[180:183], v[214:217], v[24:27]
	v_mfma_f32_16x16x32_bf16 v[16:19], v[190:193], v[214:217], v[16:19]
	v_mfma_f32_16x16x32_bf16 v[8:11], v[180:183], v[222:225], v[8:11]
	v_mfma_f32_16x16x32_bf16 v[0:3], v[190:193], v[222:225], v[0:3]
	s_setprio 0
	s_barrier
	s_add_i32 s76, 0, 0x18000
	v_add_u32_e32 v153, s76, v147
	s_add_i32 s77, 0, 0x1c000
	ds_read_b128 v[160:163], v153
	v_xor_b32_e32 v253, 64, v153
	ds_read_b128 v[164:167], v253
	ds_read_b128 v[168:171], v153 offset:2048
	ds_read_b128 v[172:175], v253 offset:2048
	v_add_u32_e32 v153, s77, v147
	ds_read_b128 v[176:179], v153
	v_xor_b32_e32 v253, 64, v153
	ds_read_b128 v[180:183], v253
	ds_read_b128 v[186:189], v153 offset:2048
	ds_read_b128 v[190:193], v253 offset:2048
	s_add_u32 s50, s50, 0x40000
	s_addc_u32 s51, s51, 0
	s_mov_b32 m0, s59
	v_lshl_add_u64 v[232:233], s[50:51], 0, v[134:135]
	ds_read_b128 v[194:197], v150 offset:32768
	v_xor_b32_e32 v253, 64, v150
	ds_read_b128 v[198:201], v253 offset:32768
	ds_read_b128 v[202:205], v150 offset:34816
	ds_read_b128 v[206:209], v253 offset:34816
	ds_read_b128 v[210:213], v150 offset:36864
	ds_read_b128 v[214:217], v253 offset:36864
	ds_read_b128 v[218:221], v150 offset:38912
	ds_read_b128 v[222:225], v253 offset:38912
	global_load_lds_dwordx4 v[232:233], off
	v_lshl_add_u64 v[232:233], s[50:51], 0, v[130:131]
	s_mov_b32 m0, s60
	s_nop 0
	global_load_lds_dwordx4 v[232:233], off
	s_waitcnt vmcnt(12)
	s_waitcnt lgkmcnt(0)
	s_barrier
	s_setprio 1
	s_waitcnt lgkmcnt(0)
	v_mfma_f32_16x16x32_bf16 v[124:127], v[160:163], v[194:197], v[124:127]
	v_mfma_f32_16x16x32_bf16 v[124:127], v[164:167], v[198:201], v[124:127]
	v_mfma_f32_16x16x32_bf16 v[116:119], v[172:175], v[198:201], v[116:119]
	v_mfma_f32_16x16x32_bf16 v[116:119], v[168:171], v[194:197], v[116:119]
	v_mfma_f32_16x16x32_bf16 v[100:103], v[168:171], v[202:205], v[100:103]
	v_mfma_f32_16x16x32_bf16 v[100:103], v[172:175], v[206:209], v[100:103]
	v_mfma_f32_16x16x32_bf16 v[108:111], v[164:167], v[206:209], v[108:111]
	v_mfma_f32_16x16x32_bf16 v[108:111], v[160:163], v[202:205], v[108:111]
	v_mfma_f32_16x16x32_bf16 v[92:95], v[160:163], v[210:213], v[92:95]
	v_mfma_f32_16x16x32_bf16 v[92:95], v[164:167], v[214:217], v[92:95]
	v_mfma_f32_16x16x32_bf16 v[84:87], v[172:175], v[214:217], v[84:87]
	v_mfma_f32_16x16x32_bf16 v[84:87], v[168:171], v[210:213], v[84:87]
	v_mfma_f32_16x16x32_bf16 v[68:71], v[168:171], v[218:221], v[68:71]
	v_mfma_f32_16x16x32_bf16 v[68:71], v[172:175], v[222:225], v[68:71]
	v_mfma_f32_16x16x32_bf16 v[76:79], v[164:167], v[222:225], v[76:79]
	v_mfma_f32_16x16x32_bf16 v[76:79], v[160:163], v[218:221], v[76:79]
	s_setprio 0
	s_setprio 1
	v_mfma_f32_16x16x32_bf16 v[120:123], v[176:179], v[194:197], v[120:123]
	v_mfma_f32_16x16x32_bf16 v[120:123], v[180:183], v[198:201], v[120:123]
	v_mfma_f32_16x16x32_bf16 v[112:115], v[190:193], v[198:201], v[112:115]
	v_mfma_f32_16x16x32_bf16 v[112:115], v[186:189], v[194:197], v[112:115]
	v_mfma_f32_16x16x32_bf16 v[96:99], v[186:189], v[202:205], v[96:99]
	v_mfma_f32_16x16x32_bf16 v[96:99], v[190:193], v[206:209], v[96:99]
	v_mfma_f32_16x16x32_bf16 v[104:107], v[180:183], v[206:209], v[104:107]
	v_mfma_f32_16x16x32_bf16 v[104:107], v[176:179], v[202:205], v[104:107]
	v_mfma_f32_16x16x32_bf16 v[88:91], v[176:179], v[210:213], v[88:91]
	v_mfma_f32_16x16x32_bf16 v[88:91], v[180:183], v[214:217], v[88:91]
	v_mfma_f32_16x16x32_bf16 v[80:83], v[190:193], v[214:217], v[80:83]
	v_mfma_f32_16x16x32_bf16 v[80:83], v[186:189], v[210:213], v[80:83]
	v_mfma_f32_16x16x32_bf16 v[64:67], v[186:189], v[218:221], v[64:67]
	v_mfma_f32_16x16x32_bf16 v[64:67], v[190:193], v[222:225], v[64:67]
	v_mfma_f32_16x16x32_bf16 v[72:75], v[180:183], v[222:225], v[72:75]
	v_mfma_f32_16x16x32_bf16 v[72:75], v[176:179], v[218:221], v[72:75]
	s_setprio 0
	s_barrier
	s_add_i32 s50, s76, s54
	v_lshl_add_u64 v[154:155], v[154:155], 0, s[20:21]
	s_mov_b32 m0, s50
	ds_read_b128 v[194:197], v150 offset:49152
	v_xor_b32_e32 v253, 64, v150
	ds_read_b128 v[198:201], v253 offset:49152
	ds_read_b128 v[202:205], v150 offset:51200
	ds_read_b128 v[206:209], v253 offset:51200
	ds_read_b128 v[210:213], v150 offset:53248
	ds_read_b128 v[214:217], v253 offset:53248
	ds_read_b128 v[218:221], v150 offset:55296
	ds_read_b128 v[222:225], v253 offset:55296
	global_load_lds_dwordx4 v[154:155], off
	s_add_i32 m0, s50, 0x2000
	s_add_u32 s48, s48, 0x40080
	v_lshl_add_u64 v[154:155], v[226:227], 0, s[20:21]
	s_addc_u32 s49, s49, 0
	s_add_i32 s50, s77, s54
	global_load_lds_dwordx4 v[154:155], off
	v_lshl_add_u64 v[154:155], s[48:49], 0, v[132:133]
	s_mov_b32 m0, s50
	s_nop 0
	global_load_lds_dwordx4 v[154:155], off
	v_lshl_add_u64 v[154:155], s[48:49], 0, v[128:129]
	s_add_i32 m0, s50, 0x2000
	s_nop 0
	global_load_lds_dwordx4 v[154:155], off
	v_lshl_add_u64 v[154:155], v[228:229], 0, s[20:21]
	s_mov_b32 m0, s62
	s_nop 0
	global_load_lds_dwordx4 v[154:155], off
	v_lshl_add_u64 v[154:155], v[230:231], 0, s[20:21]
	s_mov_b32 m0, s63
	s_nop 0
	global_load_lds_dwordx4 v[154:155], off
	s_waitcnt vmcnt(8)
	s_waitcnt lgkmcnt(0)
	s_barrier
	s_setprio 1
	s_waitcnt lgkmcnt(0)
	v_mfma_f32_16x16x32_bf16 v[60:63], v[160:163], v[194:197], v[60:63]
	v_mfma_f32_16x16x32_bf16 v[60:63], v[164:167], v[198:201], v[60:63]
	v_mfma_f32_16x16x32_bf16 v[52:55], v[172:175], v[198:201], v[52:55]
	v_mfma_f32_16x16x32_bf16 v[52:55], v[168:171], v[194:197], v[52:55]
	v_mfma_f32_16x16x32_bf16 v[36:39], v[168:171], v[202:205], v[36:39]
	v_mfma_f32_16x16x32_bf16 v[36:39], v[172:175], v[206:209], v[36:39]
	v_mfma_f32_16x16x32_bf16 v[44:47], v[164:167], v[206:209], v[44:47]
	v_mfma_f32_16x16x32_bf16 v[44:47], v[160:163], v[202:205], v[44:47]
	v_mfma_f32_16x16x32_bf16 v[28:31], v[160:163], v[210:213], v[28:31]
	v_mfma_f32_16x16x32_bf16 v[28:31], v[164:167], v[214:217], v[28:31]
	v_mfma_f32_16x16x32_bf16 v[20:23], v[172:175], v[214:217], v[20:23]
	v_mfma_f32_16x16x32_bf16 v[20:23], v[168:171], v[210:213], v[20:23]
	v_mfma_f32_16x16x32_bf16 v[4:7], v[168:171], v[218:221], v[4:7]
	v_mfma_f32_16x16x32_bf16 v[4:7], v[172:175], v[222:225], v[4:7]
	v_mfma_f32_16x16x32_bf16 v[12:15], v[164:167], v[222:225], v[12:15]
	v_mfma_f32_16x16x32_bf16 v[12:15], v[160:163], v[218:221], v[12:15]
	s_setprio 0
	s_setprio 1
	v_mfma_f32_16x16x32_bf16 v[56:59], v[176:179], v[194:197], v[56:59]
	v_mfma_f32_16x16x32_bf16 v[56:59], v[180:183], v[198:201], v[56:59]
	v_mfma_f32_16x16x32_bf16 v[48:51], v[190:193], v[198:201], v[48:51]
	v_mfma_f32_16x16x32_bf16 v[48:51], v[186:189], v[194:197], v[48:51]
	v_mfma_f32_16x16x32_bf16 v[32:35], v[186:189], v[202:205], v[32:35]
	v_mfma_f32_16x16x32_bf16 v[32:35], v[190:193], v[206:209], v[32:35]
	v_mfma_f32_16x16x32_bf16 v[40:43], v[180:183], v[206:209], v[40:43]
	v_mfma_f32_16x16x32_bf16 v[40:43], v[176:179], v[202:205], v[40:43]
	v_mfma_f32_16x16x32_bf16 v[24:27], v[176:179], v[210:213], v[24:27]
	v_mfma_f32_16x16x32_bf16 v[24:27], v[180:183], v[214:217], v[24:27]
	v_mfma_f32_16x16x32_bf16 v[16:19], v[190:193], v[214:217], v[16:19]
	v_mfma_f32_16x16x32_bf16 v[16:19], v[186:189], v[210:213], v[16:19]
	v_mfma_f32_16x16x32_bf16 v[0:3], v[186:189], v[218:221], v[0:3]
	v_mfma_f32_16x16x32_bf16 v[0:3], v[190:193], v[222:225], v[0:3]
	v_mfma_f32_16x16x32_bf16 v[8:11], v[180:183], v[222:225], v[8:11]
	v_mfma_f32_16x16x32_bf16 v[8:11], v[176:179], v[218:221], v[8:11]
	s_setprio 0
	s_barrier
	s_add_i32 s75, s75, 2
	s_add_u32 s73, s73, 0x100
	s_addc_u32 s74, s74, 0
	s_add_u32 s46, s46, 0x100
	s_addc_u32 s47, s47, 0
	s_branch .LBB0_527

.LBB0_529:
	s_and_b64 vcc, exec, s[10:11]
	s_cbranch_vccnz .LBB0_531
	s_and_b64 vcc, exec, s[24:25]
	s_cbranch_vccz .LBB0_531
	s_barrier
.LBB0_531:
	s_andn2_b64 vcc, exec, s[10:11]
	s_cbranch_vccz .Lskip_e1_4
	v_add_u32_e32 v235, 0x84000, v235
	v_add_u32_e32 v234, 0x21800, v151
	ds_read_b128 v[236:239], v234
	ds_read_b128 v[240:243], v234 offset:256
	ds_read_b128 v[244:247], v234 offset:512
	ds_read_b128 v[248:251], v234 offset:768
	s_waitcnt lgkmcnt(0)
	v_add_f32_e32 v236, v236, v237
	v_add_f32_e32 v238, v238, v239
	v_add_f32_e32 v240, v240, v241
	v_add_f32_e32 v242, v242, v243
	v_add_f32_e32 v244, v244, v245
	v_add_f32_e32 v246, v246, v247
	v_add_f32_e32 v248, v248, v249
	v_add_f32_e32 v250, v250, v251
	v_add_f32_e32 v236, v236, v238
	v_add_f32_e32 v240, v240, v242
	v_add_f32_e32 v244, v244, v246
	v_add_f32_e32 v248, v248, v250
	v_fmamk_f32 v236, v236, 0x3a800000, v152
	v_fmamk_f32 v240, v240, 0x3a800000, v152
	v_fmamk_f32 v244, v244, 0x3a800000, v152
	v_fmamk_f32 v248, v248, 0x3a800000, v152
	v_rsq_f32_e32 v236, v236
	v_rsq_f32_e32 v240, v240
	v_rsq_f32_e32 v244, v244
	v_rsq_f32_e32 v248, v248
	v_mul_f32_e32 v252, 0xbfb8aa3b, v236
	v_mul_f32_e32 v254, v236, v236
	v_rcp_f32_e32 v254, v254
	v_pk_mul_f32 v[56:57], v[60:61], v[56:57]
	v_pk_mul_f32 v[58:59], v[62:63], v[58:59]
	v_pk_mul_f32 v[48:49], v[52:53], v[48:49]
	v_pk_mul_f32 v[50:51], v[54:55], v[50:51]
	v_pk_mul_f32 v[60:61], v[60:61], v[252:253] op_sel_hi:[1,0]
	v_pk_mul_f32 v[62:63], v[62:63], v[252:253] op_sel_hi:[1,0]
	v_pk_mul_f32 v[52:53], v[52:53], v[252:253] op_sel_hi:[1,0]
	v_pk_mul_f32 v[54:55], v[54:55], v[252:253] op_sel_hi:[1,0]
	v_exp_f32_e32 v60, v60
	v_exp_f32_e32 v61, v61
	v_exp_f32_e32 v62, v62
	v_exp_f32_e32 v63, v63
	v_exp_f32_e32 v52, v52
	v_exp_f32_e32 v53, v53
	v_exp_f32_e32 v54, v54
	v_exp_f32_e32 v55, v55
	v_pk_fma_f32 v[60:61], v[60:61], v[254:255], v[254:255] op_sel_hi:[1,0,0]
	v_pk_fma_f32 v[62:63], v[62:63], v[254:255], v[254:255] op_sel_hi:[1,0,0]
	v_pk_fma_f32 v[52:53], v[52:53], v[254:255], v[254:255] op_sel_hi:[1,0,0]
	v_pk_fma_f32 v[54:55], v[54:55], v[254:255], v[254:255] op_sel_hi:[1,0,0]
	v_rcp_f32_e32 v60, v60
	v_rcp_f32_e32 v61, v61
	v_rcp_f32_e32 v62, v62
	v_rcp_f32_e32 v63, v63
	v_rcp_f32_e32 v52, v52
	v_rcp_f32_e32 v53, v53
	v_rcp_f32_e32 v54, v54
	v_rcp_f32_e32 v55, v55
	v_pk_mul_f32 v[56:57], v[56:57], v[60:61]
	v_pk_mul_f32 v[58:59], v[58:59], v[62:63]
	v_pk_mul_f32 v[48:49], v[48:49], v[52:53]
	v_pk_mul_f32 v[50:51], v[50:51], v[54:55]
	v_cvt_pk_bf16_f32 v56, v56, v57
	v_cvt_pk_bf16_f32 v57, v58, v59
	v_cvt_pk_bf16_f32 v58, v48, v49
	v_cvt_pk_bf16_f32 v59, v50, v51
	global_store_dwordx4 v235, v[56:59], s[14:15]
	v_add_u32_e32 v234, 0x16000, v235
	v_mul_f32_e32 v252, 0xbfb8aa3b, v240
	v_mul_f32_e32 v254, v240, v240
	v_rcp_f32_e32 v254, v254
	v_pk_mul_f32 v[40:41], v[44:45], v[40:41]
	v_pk_mul_f32 v[42:43], v[46:47], v[42:43]
	v_pk_mul_f32 v[32:33], v[36:37], v[32:33]
	v_pk_mul_f32 v[34:35], v[38:39], v[34:35]
	v_pk_mul_f32 v[44:45], v[44:45], v[252:253] op_sel_hi:[1,0]
	v_pk_mul_f32 v[46:47], v[46:47], v[252:253] op_sel_hi:[1,0]
	v_pk_mul_f32 v[36:37], v[36:37], v[252:253] op_sel_hi:[1,0]
	v_pk_mul_f32 v[38:39], v[38:39], v[252:253] op_sel_hi:[1,0]
	v_exp_f32_e32 v44, v44
	v_exp_f32_e32 v45, v45
	v_exp_f32_e32 v46, v46
	v_exp_f32_e32 v47, v47
	v_exp_f32_e32 v36, v36
	v_exp_f32_e32 v37, v37
	v_exp_f32_e32 v38, v38
	v_exp_f32_e32 v39, v39
	v_pk_fma_f32 v[44:45], v[44:45], v[254:255], v[254:255] op_sel_hi:[1,0,0]
	v_pk_fma_f32 v[46:47], v[46:47], v[254:255], v[254:255] op_sel_hi:[1,0,0]
	v_pk_fma_f32 v[36:37], v[36:37], v[254:255], v[254:255] op_sel_hi:[1,0,0]
	v_pk_fma_f32 v[38:39], v[38:39], v[254:255], v[254:255] op_sel_hi:[1,0,0]
	v_rcp_f32_e32 v44, v44
	v_rcp_f32_e32 v45, v45
	v_rcp_f32_e32 v46, v46
	v_rcp_f32_e32 v47, v47
	v_rcp_f32_e32 v36, v36
	v_rcp_f32_e32 v37, v37
	v_rcp_f32_e32 v38, v38
	v_rcp_f32_e32 v39, v39
	v_pk_mul_f32 v[40:41], v[40:41], v[44:45]
	v_pk_mul_f32 v[42:43], v[42:43], v[46:47]
	v_pk_mul_f32 v[32:33], v[32:33], v[36:37]
	v_pk_mul_f32 v[34:35], v[34:35], v[38:39]
	v_cvt_pk_bf16_f32 v40, v40, v41
	v_cvt_pk_bf16_f32 v41, v42, v43
	v_cvt_pk_bf16_f32 v42, v32, v33
	v_cvt_pk_bf16_f32 v43, v34, v35
	global_store_dwordx4 v234, v[40:43], s[14:15]
	v_add_u32_e32 v235, 0x16000, v234
	v_mul_f32_e32 v252, 0xbfb8aa3b, v244
	v_mul_f32_e32 v254, v244, v244
	v_rcp_f32_e32 v254, v254
	v_pk_mul_f32 v[24:25], v[28:29], v[24:25]
	v_pk_mul_f32 v[26:27], v[30:31], v[26:27]
	v_pk_mul_f32 v[16:17], v[20:21], v[16:17]
	v_pk_mul_f32 v[18:19], v[22:23], v[18:19]
	v_pk_mul_f32 v[28:29], v[28:29], v[252:253] op_sel_hi:[1,0]
	v_pk_mul_f32 v[30:31], v[30:31], v[252:253] op_sel_hi:[1,0]
	v_pk_mul_f32 v[20:21], v[20:21], v[252:253] op_sel_hi:[1,0]
	v_pk_mul_f32 v[22:23], v[22:23], v[252:253] op_sel_hi:[1,0]
	v_exp_f32_e32 v28, v28
	v_exp_f32_e32 v29, v29
	v_exp_f32_e32 v30, v30
	v_exp_f32_e32 v31, v31
	v_exp_f32_e32 v20, v20
	v_exp_f32_e32 v21, v21
	v_exp_f32_e32 v22, v22
	v_exp_f32_e32 v23, v23
	v_pk_fma_f32 v[28:29], v[28:29], v[254:255], v[254:255] op_sel_hi:[1,0,0]
	v_pk_fma_f32 v[30:31], v[30:31], v[254:255], v[254:255] op_sel_hi:[1,0,0]
	v_pk_fma_f32 v[20:21], v[20:21], v[254:255], v[254:255] op_sel_hi:[1,0,0]
	v_pk_fma_f32 v[22:23], v[22:23], v[254:255], v[254:255] op_sel_hi:[1,0,0]
	v_rcp_f32_e32 v28, v28
	v_rcp_f32_e32 v29, v29
	v_rcp_f32_e32 v30, v30
	v_rcp_f32_e32 v31, v31
	v_rcp_f32_e32 v20, v20
	v_rcp_f32_e32 v21, v21
	v_rcp_f32_e32 v22, v22
	v_rcp_f32_e32 v23, v23
	v_pk_mul_f32 v[24:25], v[24:25], v[28:29]
	v_pk_mul_f32 v[26:27], v[26:27], v[30:31]
	v_pk_mul_f32 v[16:17], v[16:17], v[20:21]
	v_pk_mul_f32 v[18:19], v[18:19], v[22:23]
	v_cvt_pk_bf16_f32 v24, v24, v25
	v_cvt_pk_bf16_f32 v25, v26, v27
	v_cvt_pk_bf16_f32 v26, v16, v17
	v_cvt_pk_bf16_f32 v27, v18, v19
	global_store_dwordx4 v235, v[24:27], s[14:15]
	v_add_u32_e32 v234, 0x16000, v235
	v_mul_f32_e32 v252, 0xbfb8aa3b, v248
	v_mul_f32_e32 v254, v248, v248
	v_rcp_f32_e32 v254, v254
	v_pk_mul_f32 v[8:9], v[12:13], v[8:9]
	v_pk_mul_f32 v[10:11], v[14:15], v[10:11]
	v_pk_mul_f32 v[0:1], v[4:5], v[0:1]
	v_pk_mul_f32 v[2:3], v[6:7], v[2:3]
	v_pk_mul_f32 v[12:13], v[12:13], v[252:253] op_sel_hi:[1,0]
	v_pk_mul_f32 v[14:15], v[14:15], v[252:253] op_sel_hi:[1,0]
	v_pk_mul_f32 v[4:5], v[4:5], v[252:253] op_sel_hi:[1,0]
	v_pk_mul_f32 v[6:7], v[6:7], v[252:253] op_sel_hi:[1,0]
	v_exp_f32_e32 v12, v12
	v_exp_f32_e32 v13, v13
	v_exp_f32_e32 v14, v14
	v_exp_f32_e32 v15, v15
	v_exp_f32_e32 v4, v4
	v_exp_f32_e32 v5, v5
	v_exp_f32_e32 v6, v6
	v_exp_f32_e32 v7, v7
	v_pk_fma_f32 v[12:13], v[12:13], v[254:255], v[254:255] op_sel_hi:[1,0,0]
	v_pk_fma_f32 v[14:15], v[14:15], v[254:255], v[254:255] op_sel_hi:[1,0,0]
	v_pk_fma_f32 v[4:5], v[4:5], v[254:255], v[254:255] op_sel_hi:[1,0,0]
	v_pk_fma_f32 v[6:7], v[6:7], v[254:255], v[254:255] op_sel_hi:[1,0,0]
	v_rcp_f32_e32 v12, v12
	v_rcp_f32_e32 v13, v13
	v_rcp_f32_e32 v14, v14
	v_rcp_f32_e32 v15, v15
	v_rcp_f32_e32 v4, v4
	v_rcp_f32_e32 v5, v5
	v_rcp_f32_e32 v6, v6
	v_rcp_f32_e32 v7, v7
	v_pk_mul_f32 v[8:9], v[8:9], v[12:13]
	v_pk_mul_f32 v[10:11], v[10:11], v[14:15]
	v_pk_mul_f32 v[0:1], v[0:1], v[4:5]
	v_pk_mul_f32 v[2:3], v[2:3], v[6:7]
	v_cvt_pk_bf16_f32 v8, v8, v9
	v_cvt_pk_bf16_f32 v9, v10, v11
	v_cvt_pk_bf16_f32 v10, v0, v1
	v_cvt_pk_bf16_f32 v11, v2, v3
	global_store_dwordx4 v234, v[8:11], s[14:15]
.Lskip_e1_4:
	s_mov_b64 s[10:11], -1
	s_cbranch_vccnz .LBB0_522
	s_andn2_b64 vcc, exec, s[12:13]
	s_cbranch_vccnz .LBB0_521
	s_branch .LBB0_521

.Lwgm_orig_4:
	s_ashr_i32 s22, s26, 31
	s_lshr_b32 s22, s22, 29
	s_add_i32 s22, s26, s22
	s_ashr_i32 s23, s22, 3
	s_and_b32 s22, s22, -8
	s_sub_i32 s22, s26, s22
	s_cmp_lt_i32 s22, 0
	s_cselect_b32 s24, s51, 0x160
	s_mul_i32 s22, s24, s22
	s_add_i32 s22, s22, s23
	s_mul_hi_i32 s23, s22, 0x2e8ba2e9
	s_lshr_b32 s24, s23, 31
	s_ashr_i32 s23, s23, 3
	s_add_i32 s23, s23, s24
	s_lshl_b32 s24, s23, 1
	s_sub_i32 s25, 0x80, s24
	s_min_i32 s25, s25, 2
	s_abs_i32 s26, s25
	v_cvt_f32_u32_e32 v250, s26
	s_sub_i32 s28, 0, s26
	s_mul_i32 s23, s23, 44
	s_sub_i32 s23, s22, s23
	v_rcp_iflag_f32_e32 v250, v250
	s_abs_i32 s22, s23
	s_xor_b32 s27, s23, s25
	s_ashr_i32 s27, s27, 31
	v_mul_f32_e32 v250, 0x4f7ffffe, v250
	v_cvt_u32_f32_e32 v250, v250
	s_nop 0
	v_readfirstlane_b32 s29, v250
	s_mul_i32 s28, s28, s29
	s_mul_hi_u32 s28, s29, s28
	s_add_i32 s29, s29, s28
	s_mul_hi_u32 s28, s22, s29
	s_mul_i32 s29, s28, s26
	s_sub_i32 s22, s22, s29
	s_add_i32 s31, s28, 1
	s_sub_i32 s29, s22, s26
	s_cmp_ge_u32 s22, s26
	s_cselect_b32 s28, s31, s28
	s_cselect_b32 s22, s29, s22
	s_add_i32 s29, s28, 1
	s_cmp_ge_u32 s22, s26
	s_cselect_b32 s22, s29, s28
	s_xor_b32 s22, s22, s27
	s_sub_i32 s22, s22, s27
	s_mul_i32 s25, s22, s25
	s_sub_i32 s23, s23, s25
	s_add_i32 s24, s23, s24
.LBB0_1096:
	s_ashr_i32 s25, s24, 31
	s_lshl_b64 s[26:27], s[24:25], 19
	s_add_u32 s26, s3, s26
	s_addc_u32 s27, s33, s27
	s_and_b64 s[28:29], s[6:7], exec
	s_cselect_b32 s25, s27, s47
	s_cselect_b32 s65, s26, s46
	s_ashr_i32 s23, s22, 31
	s_lshl_b64 s[28:29], s[22:23], 19
	s_add_u32 s28, s35, s28
	s_addc_u32 s29, s48, s29
	s_and_b64 s[66:67], s[6:7], exec
	s_cselect_b32 s66, s29, s45
	s_cselect_b32 s67, s28, s44
	s_lshl_b32 s23, s30, 8
	v_add_u32_e32 v250, s23, v148
	s_add_u32 s68, s44, 0x100
	v_ashrrev_i32_e32 v251, 31, v250
	s_addc_u32 s69, s45, 0
	v_lshl_add_u64 v[144:145], v[250:251], 4, s[12:13]
	s_add_u32 s30, s46, 0x40080
	s_addc_u32 s31, s47, 0
	s_mov_b32 s70, -2
	s_mov_b64 s[44:45], 0
	s_cmp_eq_u32 s56, 1
	s_cbranch_scc1 .Lfa_10
	v_add_u32_e32 v153, s61, v147
	ds_read_b128 v[160:163], v153
	v_xor_b32_e32 v253, 64, v153
	ds_read_b128 v[164:167], v253
	ds_read_b128 v[168:171], v153 offset:2048
	ds_read_b128 v[172:175], v253 offset:2048
	v_add_u32_e32 v153, s62, v147
	ds_read_b128 v[176:179], v153
	v_xor_b32_e32 v253, 64, v153
	ds_read_b128 v[180:183], v253
	ds_read_b128 v[184:187], v153 offset:2048
	ds_read_b128 v[188:191], v253 offset:2048
	s_add_u32 s46, s30, 0xfffc0080
	s_addc_u32 s47, s31, -1
	s_and_b64 s[44:45], s[44:45], exec
	s_cselect_b32 s47, s25, s47
	s_cselect_b32 s46, s65, s46
	s_cselect_b32 s45, s66, s69
	s_cselect_b32 s44, s67, s68
	v_lshl_add_u64 v[154:155], s[30:31], 0, v[138:139]
	s_add_i32 m0, s52, 0xc000
	ds_read_b128 v[192:195], v150
	v_xor_b32_e32 v253, 64, v150
	ds_read_b128 v[196:199], v253
	ds_read_b128 v[200:203], v150 offset:2048
	ds_read_b128 v[204:207], v253 offset:2048
	ds_read_b128 v[208:211], v150 offset:4096
	ds_read_b128 v[212:215], v253 offset:4096
	ds_read_b128 v[216:219], v150 offset:6144
	ds_read_b128 v[220:223], v253 offset:6144
	global_load_lds_dwordx4 v[154:155], off
	v_lshl_add_u64 v[154:155], s[30:31], 0, v[136:137]
	s_add_i32 m0, s52, 0xe000
	s_nop 0
	global_load_lds_dwordx4 v[154:155], off
	s_waitcnt lgkmcnt(0)
	v_add_u32_e32 v235, 0x84000, v235
	v_add_u32_e32 v234, 0x21800, v151
	ds_read_b128 v[236:239], v234
	ds_read_b128 v[240:243], v234 offset:256
	ds_read_b128 v[244:247], v234 offset:512
	ds_read_b128 v[248:251], v234 offset:768
	s_waitcnt lgkmcnt(0)
	v_add_f32_e32 v236, v236, v237
	v_add_f32_e32 v238, v238, v239
	v_add_f32_e32 v240, v240, v241
	v_add_f32_e32 v242, v242, v243
	v_add_f32_e32 v244, v244, v245
	v_add_f32_e32 v246, v246, v247
	v_add_f32_e32 v248, v248, v249
	v_add_f32_e32 v250, v250, v251
	v_add_f32_e32 v236, v236, v238
	v_add_f32_e32 v240, v240, v242
	v_add_f32_e32 v244, v244, v246
	v_add_f32_e32 v248, v248, v250
	v_fmamk_f32 v236, v236, 0x3a800000, v152
	v_fmamk_f32 v240, v240, 0x3a800000, v152
	v_fmamk_f32 v244, v244, 0x3a800000, v152
	v_fmamk_f32 v248, v248, 0x3a800000, v152
	v_rsq_f32_e32 v236, v236
	v_rsq_f32_e32 v240, v240
	v_rsq_f32_e32 v244, v244
	v_rsq_f32_e32 v248, v248
	v_mul_f32_e32 v252, 0xbfb8aa3b, v236
	v_mul_f32_e32 v254, v236, v236
	v_rcp_f32_e32 v254, v254
	v_pk_mul_f32 v[56:57], v[60:61], v[56:57]
	v_pk_mul_f32 v[58:59], v[62:63], v[58:59]
	v_pk_mul_f32 v[48:49], v[52:53], v[48:49]
	v_pk_mul_f32 v[50:51], v[54:55], v[50:51]
	v_pk_mul_f32 v[60:61], v[60:61], v[252:253] op_sel_hi:[1,0]
	v_pk_mul_f32 v[62:63], v[62:63], v[252:253] op_sel_hi:[1,0]
	v_pk_mul_f32 v[52:53], v[52:53], v[252:253] op_sel_hi:[1,0]
	v_pk_mul_f32 v[54:55], v[54:55], v[252:253] op_sel_hi:[1,0]
	v_exp_f32_e32 v60, v60
	v_exp_f32_e32 v61, v61
	v_exp_f32_e32 v62, v62
	v_exp_f32_e32 v63, v63
	v_exp_f32_e32 v52, v52
	v_exp_f32_e32 v53, v53
	v_exp_f32_e32 v54, v54
	v_exp_f32_e32 v55, v55
	v_pk_fma_f32 v[60:61], v[60:61], v[254:255], v[254:255] op_sel_hi:[1,0,0]
	v_pk_fma_f32 v[62:63], v[62:63], v[254:255], v[254:255] op_sel_hi:[1,0,0]
	v_pk_fma_f32 v[52:53], v[52:53], v[254:255], v[254:255] op_sel_hi:[1,0,0]
	v_pk_fma_f32 v[54:55], v[54:55], v[254:255], v[254:255] op_sel_hi:[1,0,0]
	v_rcp_f32_e32 v60, v60
	v_rcp_f32_e32 v61, v61
	v_rcp_f32_e32 v62, v62
	v_rcp_f32_e32 v63, v63
	v_rcp_f32_e32 v52, v52
	v_rcp_f32_e32 v53, v53
	v_rcp_f32_e32 v54, v54
	v_rcp_f32_e32 v55, v55
	v_pk_mul_f32 v[56:57], v[56:57], v[60:61]
	v_pk_mul_f32 v[58:59], v[58:59], v[62:63]
	v_pk_mul_f32 v[48:49], v[48:49], v[52:53]
	v_pk_mul_f32 v[50:51], v[50:51], v[54:55]
	v_cvt_pk_bf16_f32 v56, v56, v57
	v_cvt_pk_bf16_f32 v57, v58, v59
	v_cvt_pk_bf16_f32 v58, v48, v49
	v_cvt_pk_bf16_f32 v59, v50, v51
	global_store_dwordx4 v235, v[56:59], s[10:11]
	v_add_u32_e32 v234, 0x16000, v235
	v_mul_f32_e32 v252, 0xbfb8aa3b, v240
	v_mul_f32_e32 v254, v240, v240
	v_rcp_f32_e32 v254, v254
	v_pk_mul_f32 v[40:41], v[44:45], v[40:41]
	v_pk_mul_f32 v[42:43], v[46:47], v[42:43]
	v_pk_mul_f32 v[32:33], v[36:37], v[32:33]
	v_pk_mul_f32 v[34:35], v[38:39], v[34:35]
	v_pk_mul_f32 v[44:45], v[44:45], v[252:253] op_sel_hi:[1,0]
	v_pk_mul_f32 v[46:47], v[46:47], v[252:253] op_sel_hi:[1,0]
	v_pk_mul_f32 v[36:37], v[36:37], v[252:253] op_sel_hi:[1,0]
	v_pk_mul_f32 v[38:39], v[38:39], v[252:253] op_sel_hi:[1,0]
	v_exp_f32_e32 v44, v44
	v_exp_f32_e32 v45, v45
	v_exp_f32_e32 v46, v46
	v_exp_f32_e32 v47, v47
	v_exp_f32_e32 v36, v36
	v_exp_f32_e32 v37, v37
	v_exp_f32_e32 v38, v38
	v_exp_f32_e32 v39, v39
	v_pk_fma_f32 v[44:45], v[44:45], v[254:255], v[254:255] op_sel_hi:[1,0,0]
	v_pk_fma_f32 v[46:47], v[46:47], v[254:255], v[254:255] op_sel_hi:[1,0,0]
	v_pk_fma_f32 v[36:37], v[36:37], v[254:255], v[254:255] op_sel_hi:[1,0,0]
	v_pk_fma_f32 v[38:39], v[38:39], v[254:255], v[254:255] op_sel_hi:[1,0,0]
	v_rcp_f32_e32 v44, v44
	v_rcp_f32_e32 v45, v45
	v_rcp_f32_e32 v46, v46
	v_rcp_f32_e32 v47, v47
	v_rcp_f32_e32 v36, v36
	v_rcp_f32_e32 v37, v37
	v_rcp_f32_e32 v38, v38
	v_rcp_f32_e32 v39, v39
	v_pk_mul_f32 v[40:41], v[40:41], v[44:45]
	v_pk_mul_f32 v[42:43], v[42:43], v[46:47]
	v_pk_mul_f32 v[32:33], v[32:33], v[36:37]
	v_pk_mul_f32 v[34:35], v[34:35], v[38:39]
	v_cvt_pk_bf16_f32 v40, v40, v41
	v_cvt_pk_bf16_f32 v41, v42, v43
	v_cvt_pk_bf16_f32 v42, v32, v33
	v_cvt_pk_bf16_f32 v43, v34, v35
	global_store_dwordx4 v234, v[40:43], s[10:11]
	v_add_u32_e32 v235, 0x16000, v234
	v_mul_f32_e32 v252, 0xbfb8aa3b, v244
	v_mul_f32_e32 v254, v244, v244
	v_rcp_f32_e32 v254, v254
	v_pk_mul_f32 v[24:25], v[28:29], v[24:25]
	v_pk_mul_f32 v[26:27], v[30:31], v[26:27]
	v_pk_mul_f32 v[16:17], v[20:21], v[16:17]
	v_pk_mul_f32 v[18:19], v[22:23], v[18:19]
	v_pk_mul_f32 v[28:29], v[28:29], v[252:253] op_sel_hi:[1,0]
	v_pk_mul_f32 v[30:31], v[30:31], v[252:253] op_sel_hi:[1,0]
	v_pk_mul_f32 v[20:21], v[20:21], v[252:253] op_sel_hi:[1,0]
	v_pk_mul_f32 v[22:23], v[22:23], v[252:253] op_sel_hi:[1,0]
	v_exp_f32_e32 v28, v28
	v_exp_f32_e32 v29, v29
	v_exp_f32_e32 v30, v30
	v_exp_f32_e32 v31, v31
	v_exp_f32_e32 v20, v20
	v_exp_f32_e32 v21, v21
	v_exp_f32_e32 v22, v22
	v_exp_f32_e32 v23, v23
	v_pk_fma_f32 v[28:29], v[28:29], v[254:255], v[254:255] op_sel_hi:[1,0,0]
	v_pk_fma_f32 v[30:31], v[30:31], v[254:255], v[254:255] op_sel_hi:[1,0,0]
	v_pk_fma_f32 v[20:21], v[20:21], v[254:255], v[254:255] op_sel_hi:[1,0,0]
	v_pk_fma_f32 v[22:23], v[22:23], v[254:255], v[254:255] op_sel_hi:[1,0,0]
	v_rcp_f32_e32 v28, v28
	v_rcp_f32_e32 v29, v29
	v_rcp_f32_e32 v30, v30
	v_rcp_f32_e32 v31, v31
	v_rcp_f32_e32 v20, v20
	v_rcp_f32_e32 v21, v21
	v_rcp_f32_e32 v22, v22
	v_rcp_f32_e32 v23, v23
	v_pk_mul_f32 v[24:25], v[24:25], v[28:29]
	v_pk_mul_f32 v[26:27], v[26:27], v[30:31]
	v_pk_mul_f32 v[16:17], v[16:17], v[20:21]
	v_pk_mul_f32 v[18:19], v[18:19], v[22:23]
	v_cvt_pk_bf16_f32 v24, v24, v25
	v_cvt_pk_bf16_f32 v25, v26, v27
	v_cvt_pk_bf16_f32 v26, v16, v17
	v_cvt_pk_bf16_f32 v27, v18, v19
	global_store_dwordx4 v235, v[24:27], s[10:11]
	v_add_u32_e32 v234, 0x16000, v235
	v_mul_f32_e32 v252, 0xbfb8aa3b, v248
	v_mul_f32_e32 v254, v248, v248
	v_rcp_f32_e32 v254, v254
	v_pk_mul_f32 v[8:9], v[12:13], v[8:9]
	v_pk_mul_f32 v[10:11], v[14:15], v[10:11]
	v_pk_mul_f32 v[0:1], v[4:5], v[0:1]
	v_pk_mul_f32 v[2:3], v[6:7], v[2:3]
	v_pk_mul_f32 v[12:13], v[12:13], v[252:253] op_sel_hi:[1,0]
	v_pk_mul_f32 v[14:15], v[14:15], v[252:253] op_sel_hi:[1,0]
	v_pk_mul_f32 v[4:5], v[4:5], v[252:253] op_sel_hi:[1,0]
	v_pk_mul_f32 v[6:7], v[6:7], v[252:253] op_sel_hi:[1,0]
	v_exp_f32_e32 v12, v12
	v_exp_f32_e32 v13, v13
	v_exp_f32_e32 v14, v14
	v_exp_f32_e32 v15, v15
	v_exp_f32_e32 v4, v4
	v_exp_f32_e32 v5, v5
	v_exp_f32_e32 v6, v6
	v_exp_f32_e32 v7, v7
	v_pk_fma_f32 v[12:13], v[12:13], v[254:255], v[254:255] op_sel_hi:[1,0,0]
	v_pk_fma_f32 v[14:15], v[14:15], v[254:255], v[254:255] op_sel_hi:[1,0,0]
	v_pk_fma_f32 v[4:5], v[4:5], v[254:255], v[254:255] op_sel_hi:[1,0,0]
	v_pk_fma_f32 v[6:7], v[6:7], v[254:255], v[254:255] op_sel_hi:[1,0,0]
	v_rcp_f32_e32 v12, v12
	v_rcp_f32_e32 v13, v13
	v_rcp_f32_e32 v14, v14
	v_rcp_f32_e32 v15, v15
	v_rcp_f32_e32 v4, v4
	v_rcp_f32_e32 v5, v5
	v_rcp_f32_e32 v6, v6
	v_rcp_f32_e32 v7, v7
	v_pk_mul_f32 v[8:9], v[8:9], v[12:13]
	v_pk_mul_f32 v[10:11], v[10:11], v[14:15]
	v_pk_mul_f32 v[0:1], v[0:1], v[4:5]
	v_pk_mul_f32 v[2:3], v[2:3], v[6:7]
	v_cvt_pk_bf16_f32 v8, v8, v9
	v_cvt_pk_bf16_f32 v9, v10, v11
	v_cvt_pk_bf16_f32 v10, v0, v1
	v_cvt_pk_bf16_f32 v11, v2, v3
	global_store_dwordx4 v234, v[8:11], s[10:11]
	s_waitcnt vmcnt(16)
	s_waitcnt lgkmcnt(0)
	s_barrier
	s_setprio 1
	s_waitcnt lgkmcnt(0)
	v_mfma_f32_16x16x32_bf16 v[124:127], v[160:163], v[192:195], 0
	v_mfma_f32_16x16x32_bf16 v[116:119], v[168:171], v[192:195], 0
	v_mfma_f32_16x16x32_bf16 v[108:111], v[160:163], v[200:203], 0
	v_mfma_f32_16x16x32_bf16 v[100:103], v[168:171], v[200:203], 0
	v_mfma_f32_16x16x32_bf16 v[92:95], v[160:163], v[208:211], 0
	v_mfma_f32_16x16x32_bf16 v[84:87], v[168:171], v[208:211], 0
	v_mfma_f32_16x16x32_bf16 v[76:79], v[160:163], v[216:219], 0
	v_mfma_f32_16x16x32_bf16 v[68:71], v[168:171], v[216:219], 0
	v_mfma_f32_16x16x32_bf16 v[124:127], v[164:167], v[196:199], v[124:127]
	v_mfma_f32_16x16x32_bf16 v[116:119], v[172:175], v[196:199], v[116:119]
	v_mfma_f32_16x16x32_bf16 v[108:111], v[164:167], v[204:207], v[108:111]
	v_mfma_f32_16x16x32_bf16 v[100:103], v[172:175], v[204:207], v[100:103]
	v_mfma_f32_16x16x32_bf16 v[92:95], v[164:167], v[212:215], v[92:95]
	v_mfma_f32_16x16x32_bf16 v[84:87], v[172:175], v[212:215], v[84:87]
	v_mfma_f32_16x16x32_bf16 v[76:79], v[164:167], v[220:223], v[76:79]
	v_mfma_f32_16x16x32_bf16 v[68:71], v[172:175], v[220:223], v[68:71]
	s_setprio 0
	s_setprio 1
	v_mfma_f32_16x16x32_bf16 v[120:123], v[176:179], v[192:195], 0
	v_mfma_f32_16x16x32_bf16 v[112:115], v[184:187], v[192:195], 0
	v_mfma_f32_16x16x32_bf16 v[104:107], v[176:179], v[200:203], 0
	v_mfma_f32_16x16x32_bf16 v[96:99], v[184:187], v[200:203], 0
	v_mfma_f32_16x16x32_bf16 v[88:91], v[176:179], v[208:211], 0
	v_mfma_f32_16x16x32_bf16 v[80:83], v[184:187], v[208:211], 0
	v_mfma_f32_16x16x32_bf16 v[72:75], v[176:179], v[216:219], 0
	v_mfma_f32_16x16x32_bf16 v[64:67], v[184:187], v[216:219], 0
	v_mfma_f32_16x16x32_bf16 v[120:123], v[180:183], v[196:199], v[120:123]
	v_mfma_f32_16x16x32_bf16 v[112:115], v[188:191], v[196:199], v[112:115]
	v_mfma_f32_16x16x32_bf16 v[104:107], v[180:183], v[204:207], v[104:107]
	v_mfma_f32_16x16x32_bf16 v[96:99], v[188:191], v[204:207], v[96:99]
	v_mfma_f32_16x16x32_bf16 v[88:91], v[180:183], v[212:215], v[88:91]
	v_mfma_f32_16x16x32_bf16 v[80:83], v[188:191], v[212:215], v[80:83]
	v_mfma_f32_16x16x32_bf16 v[72:75], v[180:183], v[220:223], v[72:75]
	v_mfma_f32_16x16x32_bf16 v[64:67], v[188:191], v[220:223], v[64:67]
	s_setprio 0
	s_barrier
	s_add_i32 s71, s61, s49
	v_lshl_add_u64 v[154:155], s[44:45], 0, v[132:133]
	s_mov_b32 m0, s71
	ds_read_b128 v[192:195], v150 offset:16384
	v_xor_b32_e32 v253, 64, v150
	ds_read_b128 v[196:199], v253 offset:16384
	ds_read_b128 v[200:203], v150 offset:18432
	ds_read_b128 v[204:207], v253 offset:18432
	ds_read_b128 v[208:211], v150 offset:20480
	ds_read_b128 v[212:215], v253 offset:20480
	ds_read_b128 v[216:219], v150 offset:22528
	ds_read_b128 v[220:223], v253 offset:22528
	global_load_lds_dwordx4 v[154:155], off
	s_add_i32 m0, s71, 0x2000
	s_add_u32 s72, s44, 0x40000
	v_lshl_add_u64 v[224:225], s[44:45], 0, v[128:129]
	s_addc_u32 s73, s45, 0
	s_add_i32 s71, s62, s49
	global_load_lds_dwordx4 v[224:225], off
	v_lshl_add_u64 v[226:227], s[72:73], 0, v[132:133]
	s_mov_b32 m0, s71
	v_lshl_add_u64 v[228:229], s[46:47], 0, v[130:131]
	global_load_lds_dwordx4 v[226:227], off
	v_lshl_add_u64 v[226:227], s[72:73], 0, v[128:129]
	s_add_i32 m0, s71, 0x2000
	s_nop 0
	global_load_lds_dwordx4 v[226:227], off
	v_lshl_add_u64 v[226:227], s[46:47], 0, v[134:135]
	s_mov_b32 m0, s52
	s_nop 0
	global_load_lds_dwordx4 v[226:227], off
	s_mov_b32 m0, s53
	s_nop 0
	global_load_lds_dwordx4 v[228:229], off
	s_waitcnt vmcnt(16)
	s_waitcnt lgkmcnt(0)
	s_barrier
	s_setprio 1
	s_waitcnt lgkmcnt(0)
	v_mfma_f32_16x16x32_bf16 v[60:63], v[160:163], v[192:195], 0
	v_mfma_f32_16x16x32_bf16 v[52:55], v[168:171], v[192:195], 0
	v_mfma_f32_16x16x32_bf16 v[44:47], v[160:163], v[200:203], 0
	v_mfma_f32_16x16x32_bf16 v[36:39], v[168:171], v[200:203], 0
	v_mfma_f32_16x16x32_bf16 v[28:31], v[160:163], v[208:211], 0
	v_mfma_f32_16x16x32_bf16 v[20:23], v[168:171], v[208:211], 0
	v_mfma_f32_16x16x32_bf16 v[12:15], v[160:163], v[216:219], 0
	v_mfma_f32_16x16x32_bf16 v[4:7], v[168:171], v[216:219], 0
	v_mfma_f32_16x16x32_bf16 v[60:63], v[164:167], v[196:199], v[60:63]
	v_mfma_f32_16x16x32_bf16 v[52:55], v[172:175], v[196:199], v[52:55]
	v_mfma_f32_16x16x32_bf16 v[44:47], v[164:167], v[204:207], v[44:47]
	v_mfma_f32_16x16x32_bf16 v[36:39], v[172:175], v[204:207], v[36:39]
	v_mfma_f32_16x16x32_bf16 v[28:31], v[164:167], v[212:215], v[28:31]
	v_mfma_f32_16x16x32_bf16 v[20:23], v[172:175], v[212:215], v[20:23]
	v_mfma_f32_16x16x32_bf16 v[12:15], v[164:167], v[220:223], v[12:15]
	v_mfma_f32_16x16x32_bf16 v[4:7], v[172:175], v[220:223], v[4:7]
	s_setprio 0
	s_setprio 1
	v_mfma_f32_16x16x32_bf16 v[56:59], v[176:179], v[192:195], 0
	v_mfma_f32_16x16x32_bf16 v[48:51], v[184:187], v[192:195], 0
	v_mfma_f32_16x16x32_bf16 v[40:43], v[176:179], v[200:203], 0
	v_mfma_f32_16x16x32_bf16 v[32:35], v[184:187], v[200:203], 0
	v_mfma_f32_16x16x32_bf16 v[24:27], v[176:179], v[208:211], 0
	v_mfma_f32_16x16x32_bf16 v[16:19], v[184:187], v[208:211], 0
	v_mfma_f32_16x16x32_bf16 v[8:11], v[176:179], v[216:219], 0
	v_mfma_f32_16x16x32_bf16 v[0:3], v[184:187], v[216:219], 0
	v_mfma_f32_16x16x32_bf16 v[56:59], v[180:183], v[196:199], v[56:59]
	v_mfma_f32_16x16x32_bf16 v[48:51], v[188:191], v[196:199], v[48:51]
	v_mfma_f32_16x16x32_bf16 v[40:43], v[180:183], v[204:207], v[40:43]
	v_mfma_f32_16x16x32_bf16 v[32:35], v[188:191], v[204:207], v[32:35]
	v_mfma_f32_16x16x32_bf16 v[24:27], v[180:183], v[212:215], v[24:27]
	v_mfma_f32_16x16x32_bf16 v[16:19], v[188:191], v[212:215], v[16:19]
	v_mfma_f32_16x16x32_bf16 v[8:11], v[180:183], v[220:223], v[8:11]
	v_mfma_f32_16x16x32_bf16 v[0:3], v[188:191], v[220:223], v[0:3]
	s_setprio 0
	s_barrier
	s_add_i32 s71, 0, 0x18000
	v_add_u32_e32 v153, s71, v147
	s_add_i32 s72, 0, 0x1c000
	ds_read_b128 v[160:163], v153
	v_xor_b32_e32 v253, 64, v153
	ds_read_b128 v[164:167], v253
	ds_read_b128 v[168:171], v153 offset:2048
	ds_read_b128 v[172:175], v253 offset:2048
	v_add_u32_e32 v153, s72, v147
	ds_read_b128 v[176:179], v153
	v_xor_b32_e32 v253, 64, v153
	ds_read_b128 v[180:183], v253
	ds_read_b128 v[184:187], v153 offset:2048
	ds_read_b128 v[188:191], v253 offset:2048
	s_add_u32 s46, s46, 0x40000
	s_addc_u32 s47, s47, 0
	s_mov_b32 m0, s54
	v_lshl_add_u64 v[230:231], s[46:47], 0, v[134:135]
	ds_read_b128 v[192:195], v150 offset:32768
	v_xor_b32_e32 v253, 64, v150
	ds_read_b128 v[196:199], v253 offset:32768
	ds_read_b128 v[200:203], v150 offset:34816
	ds_read_b128 v[204:207], v253 offset:34816
	ds_read_b128 v[208:211], v150 offset:36864
	ds_read_b128 v[212:215], v253 offset:36864
	ds_read_b128 v[216:219], v150 offset:38912
	ds_read_b128 v[220:223], v253 offset:38912
	global_load_lds_dwordx4 v[230:231], off
	v_lshl_add_u64 v[230:231], s[46:47], 0, v[130:131]
	s_mov_b32 m0, s55
	s_nop 0
	global_load_lds_dwordx4 v[230:231], off
	s_waitcnt vmcnt(12)
	s_waitcnt lgkmcnt(0)
	s_barrier
	s_setprio 1
	s_waitcnt lgkmcnt(0)
	v_mfma_f32_16x16x32_bf16 v[124:127], v[160:163], v[192:195], v[124:127]
	v_mfma_f32_16x16x32_bf16 v[124:127], v[164:167], v[196:199], v[124:127]
	v_mfma_f32_16x16x32_bf16 v[116:119], v[172:175], v[196:199], v[116:119]
	v_mfma_f32_16x16x32_bf16 v[116:119], v[168:171], v[192:195], v[116:119]
	v_mfma_f32_16x16x32_bf16 v[100:103], v[168:171], v[200:203], v[100:103]
	v_mfma_f32_16x16x32_bf16 v[100:103], v[172:175], v[204:207], v[100:103]
	v_mfma_f32_16x16x32_bf16 v[108:111], v[164:167], v[204:207], v[108:111]
	v_mfma_f32_16x16x32_bf16 v[108:111], v[160:163], v[200:203], v[108:111]
	v_mfma_f32_16x16x32_bf16 v[92:95], v[160:163], v[208:211], v[92:95]
	v_mfma_f32_16x16x32_bf16 v[92:95], v[164:167], v[212:215], v[92:95]
	v_mfma_f32_16x16x32_bf16 v[84:87], v[172:175], v[212:215], v[84:87]
	v_mfma_f32_16x16x32_bf16 v[84:87], v[168:171], v[208:211], v[84:87]
	v_mfma_f32_16x16x32_bf16 v[68:71], v[168:171], v[216:219], v[68:71]
	v_mfma_f32_16x16x32_bf16 v[68:71], v[172:175], v[220:223], v[68:71]
	v_mfma_f32_16x16x32_bf16 v[76:79], v[164:167], v[220:223], v[76:79]
	v_mfma_f32_16x16x32_bf16 v[76:79], v[160:163], v[216:219], v[76:79]
	s_setprio 0
	s_setprio 1
	v_mfma_f32_16x16x32_bf16 v[120:123], v[176:179], v[192:195], v[120:123]
	v_mfma_f32_16x16x32_bf16 v[120:123], v[180:183], v[196:199], v[120:123]
	v_mfma_f32_16x16x32_bf16 v[112:115], v[188:191], v[196:199], v[112:115]
	v_mfma_f32_16x16x32_bf16 v[112:115], v[184:187], v[192:195], v[112:115]
	v_mfma_f32_16x16x32_bf16 v[96:99], v[184:187], v[200:203], v[96:99]
	v_mfma_f32_16x16x32_bf16 v[96:99], v[188:191], v[204:207], v[96:99]
	v_mfma_f32_16x16x32_bf16 v[104:107], v[180:183], v[204:207], v[104:107]
	v_mfma_f32_16x16x32_bf16 v[104:107], v[176:179], v[200:203], v[104:107]
	v_mfma_f32_16x16x32_bf16 v[88:91], v[176:179], v[208:211], v[88:91]
	v_mfma_f32_16x16x32_bf16 v[88:91], v[180:183], v[212:215], v[88:91]
	v_mfma_f32_16x16x32_bf16 v[80:83], v[188:191], v[212:215], v[80:83]
	v_mfma_f32_16x16x32_bf16 v[80:83], v[184:187], v[208:211], v[80:83]
	v_mfma_f32_16x16x32_bf16 v[64:67], v[184:187], v[216:219], v[64:67]
	v_mfma_f32_16x16x32_bf16 v[64:67], v[188:191], v[220:223], v[64:67]
	v_mfma_f32_16x16x32_bf16 v[72:75], v[180:183], v[220:223], v[72:75]
	v_mfma_f32_16x16x32_bf16 v[72:75], v[176:179], v[216:219], v[72:75]
	s_setprio 0
	s_barrier
	s_add_i32 s46, s71, s49
	v_lshl_add_u64 v[154:155], v[154:155], 0, s[14:15]
	s_mov_b32 m0, s46
	ds_read_b128 v[192:195], v150 offset:49152
	v_xor_b32_e32 v253, 64, v150
	ds_read_b128 v[196:199], v253 offset:49152
	ds_read_b128 v[200:203], v150 offset:51200
	ds_read_b128 v[204:207], v253 offset:51200
	ds_read_b128 v[208:211], v150 offset:53248
	ds_read_b128 v[212:215], v253 offset:53248
	ds_read_b128 v[216:219], v150 offset:55296
	ds_read_b128 v[220:223], v253 offset:55296
	global_load_lds_dwordx4 v[154:155], off
	s_add_i32 m0, s46, 0x2000
	s_add_u32 s44, s44, 0x40080
	v_lshl_add_u64 v[154:155], v[224:225], 0, s[14:15]
	s_addc_u32 s45, s45, 0
	s_add_i32 s46, s72, s49
	global_load_lds_dwordx4 v[154:155], off
	v_lshl_add_u64 v[154:155], s[44:45], 0, v[132:133]
	s_mov_b32 m0, s46
	s_nop 0
	global_load_lds_dwordx4 v[154:155], off
	v_lshl_add_u64 v[154:155], s[44:45], 0, v[128:129]
	s_add_i32 m0, s46, 0x2000
	s_nop 0
	global_load_lds_dwordx4 v[154:155], off
	v_lshl_add_u64 v[154:155], v[226:227], 0, s[14:15]
	s_mov_b32 m0, s57
	s_nop 0
	global_load_lds_dwordx4 v[154:155], off
	v_lshl_add_u64 v[154:155], v[228:229], 0, s[14:15]
	s_mov_b32 m0, s58
	s_nop 0
	global_load_lds_dwordx4 v[154:155], off
	s_waitcnt vmcnt(8)
	s_waitcnt lgkmcnt(0)
	s_barrier
	s_setprio 1
	s_waitcnt lgkmcnt(0)
	v_mfma_f32_16x16x32_bf16 v[60:63], v[160:163], v[192:195], v[60:63]
	v_mfma_f32_16x16x32_bf16 v[60:63], v[164:167], v[196:199], v[60:63]
	v_mfma_f32_16x16x32_bf16 v[52:55], v[172:175], v[196:199], v[52:55]
	v_mfma_f32_16x16x32_bf16 v[52:55], v[168:171], v[192:195], v[52:55]
	v_mfma_f32_16x16x32_bf16 v[36:39], v[168:171], v[200:203], v[36:39]
	v_mfma_f32_16x16x32_bf16 v[36:39], v[172:175], v[204:207], v[36:39]
	v_mfma_f32_16x16x32_bf16 v[44:47], v[164:167], v[204:207], v[44:47]
	v_mfma_f32_16x16x32_bf16 v[44:47], v[160:163], v[200:203], v[44:47]
	v_mfma_f32_16x16x32_bf16 v[28:31], v[160:163], v[208:211], v[28:31]
	v_mfma_f32_16x16x32_bf16 v[28:31], v[164:167], v[212:215], v[28:31]
	v_mfma_f32_16x16x32_bf16 v[20:23], v[172:175], v[212:215], v[20:23]
	v_mfma_f32_16x16x32_bf16 v[20:23], v[168:171], v[208:211], v[20:23]
	v_mfma_f32_16x16x32_bf16 v[4:7], v[168:171], v[216:219], v[4:7]
	v_mfma_f32_16x16x32_bf16 v[4:7], v[172:175], v[220:223], v[4:7]
	v_mfma_f32_16x16x32_bf16 v[12:15], v[164:167], v[220:223], v[12:15]
	v_mfma_f32_16x16x32_bf16 v[12:15], v[160:163], v[216:219], v[12:15]
	s_setprio 0
	s_setprio 1
	v_mfma_f32_16x16x32_bf16 v[56:59], v[176:179], v[192:195], v[56:59]
	v_mfma_f32_16x16x32_bf16 v[56:59], v[180:183], v[196:199], v[56:59]
	v_mfma_f32_16x16x32_bf16 v[48:51], v[188:191], v[196:199], v[48:51]
	v_mfma_f32_16x16x32_bf16 v[48:51], v[184:187], v[192:195], v[48:51]
	v_mfma_f32_16x16x32_bf16 v[32:35], v[184:187], v[200:203], v[32:35]
	v_mfma_f32_16x16x32_bf16 v[32:35], v[188:191], v[204:207], v[32:35]
	v_mfma_f32_16x16x32_bf16 v[40:43], v[180:183], v[204:207], v[40:43]
	v_mfma_f32_16x16x32_bf16 v[40:43], v[176:179], v[200:203], v[40:43]
	v_mfma_f32_16x16x32_bf16 v[24:27], v[176:179], v[208:211], v[24:27]
	v_mfma_f32_16x16x32_bf16 v[24:27], v[180:183], v[212:215], v[24:27]
	v_mfma_f32_16x16x32_bf16 v[16:19], v[188:191], v[212:215], v[16:19]
	v_mfma_f32_16x16x32_bf16 v[16:19], v[184:187], v[208:211], v[16:19]
	v_mfma_f32_16x16x32_bf16 v[0:3], v[184:187], v[216:219], v[0:3]
	v_mfma_f32_16x16x32_bf16 v[0:3], v[188:191], v[220:223], v[0:3]
	v_mfma_f32_16x16x32_bf16 v[8:11], v[180:183], v[220:223], v[8:11]
	v_mfma_f32_16x16x32_bf16 v[8:11], v[176:179], v[216:219], v[8:11]
	s_setprio 0
	s_barrier
	s_add_i32 s70, s70, 2
	s_add_u32 s68, s68, 0x100
	s_addc_u32 s69, s69, 0
	s_add_u32 s30, s30, 0x100
	s_addc_u32 s31, s31, 0
	s_branch .LBB0_1098

.LBB0_1100:
	s_and_b64 vcc, exec, s[6:7]
	s_cbranch_vccnz .LBB0_1102
	s_and_b64 vcc, exec, s[20:21]
	s_cbranch_vccz .LBB0_1102
	s_barrier
.LBB0_1102:
	s_andn2_b64 vcc, exec, s[6:7]
	s_cbranch_vccz .Lskip_e1_10
	v_add_u32_e32 v235, 0x84000, v235
	v_add_u32_e32 v234, 0x21800, v151
	ds_read_b128 v[236:239], v234
	ds_read_b128 v[240:243], v234 offset:256
	ds_read_b128 v[244:247], v234 offset:512
	ds_read_b128 v[248:251], v234 offset:768
	s_waitcnt lgkmcnt(0)
	v_add_f32_e32 v236, v236, v237
	v_add_f32_e32 v238, v238, v239
	v_add_f32_e32 v240, v240, v241
	v_add_f32_e32 v242, v242, v243
	v_add_f32_e32 v244, v244, v245
	v_add_f32_e32 v246, v246, v247
	v_add_f32_e32 v248, v248, v249
	v_add_f32_e32 v250, v250, v251
	v_add_f32_e32 v236, v236, v238
	v_add_f32_e32 v240, v240, v242
	v_add_f32_e32 v244, v244, v246
	v_add_f32_e32 v248, v248, v250
	v_fmamk_f32 v236, v236, 0x3a800000, v152
	v_fmamk_f32 v240, v240, 0x3a800000, v152
	v_fmamk_f32 v244, v244, 0x3a800000, v152
	v_fmamk_f32 v248, v248, 0x3a800000, v152
	v_rsq_f32_e32 v236, v236
	v_rsq_f32_e32 v240, v240
	v_rsq_f32_e32 v244, v244
	v_rsq_f32_e32 v248, v248
	v_mul_f32_e32 v252, 0xbfb8aa3b, v236
	v_mul_f32_e32 v254, v236, v236
	v_rcp_f32_e32 v254, v254
	v_pk_mul_f32 v[56:57], v[60:61], v[56:57]
	v_pk_mul_f32 v[58:59], v[62:63], v[58:59]
	v_pk_mul_f32 v[48:49], v[52:53], v[48:49]
	v_pk_mul_f32 v[50:51], v[54:55], v[50:51]
	v_pk_mul_f32 v[60:61], v[60:61], v[252:253] op_sel_hi:[1,0]
	v_pk_mul_f32 v[62:63], v[62:63], v[252:253] op_sel_hi:[1,0]
	v_pk_mul_f32 v[52:53], v[52:53], v[252:253] op_sel_hi:[1,0]
	v_pk_mul_f32 v[54:55], v[54:55], v[252:253] op_sel_hi:[1,0]
	v_exp_f32_e32 v60, v60
	v_exp_f32_e32 v61, v61
	v_exp_f32_e32 v62, v62
	v_exp_f32_e32 v63, v63
	v_exp_f32_e32 v52, v52
	v_exp_f32_e32 v53, v53
	v_exp_f32_e32 v54, v54
	v_exp_f32_e32 v55, v55
	v_pk_fma_f32 v[60:61], v[60:61], v[254:255], v[254:255] op_sel_hi:[1,0,0]
	v_pk_fma_f32 v[62:63], v[62:63], v[254:255], v[254:255] op_sel_hi:[1,0,0]
	v_pk_fma_f32 v[52:53], v[52:53], v[254:255], v[254:255] op_sel_hi:[1,0,0]
	v_pk_fma_f32 v[54:55], v[54:55], v[254:255], v[254:255] op_sel_hi:[1,0,0]
	v_rcp_f32_e32 v60, v60
	v_rcp_f32_e32 v61, v61
	v_rcp_f32_e32 v62, v62
	v_rcp_f32_e32 v63, v63
	v_rcp_f32_e32 v52, v52
	v_rcp_f32_e32 v53, v53
	v_rcp_f32_e32 v54, v54
	v_rcp_f32_e32 v55, v55
	v_pk_mul_f32 v[56:57], v[56:57], v[60:61]
	v_pk_mul_f32 v[58:59], v[58:59], v[62:63]
	v_pk_mul_f32 v[48:49], v[48:49], v[52:53]
	v_pk_mul_f32 v[50:51], v[50:51], v[54:55]
	v_cvt_pk_bf16_f32 v56, v56, v57
	v_cvt_pk_bf16_f32 v57, v58, v59
	v_cvt_pk_bf16_f32 v58, v48, v49
	v_cvt_pk_bf16_f32 v59, v50, v51
	global_store_dwordx4 v235, v[56:59], s[10:11]
	v_add_u32_e32 v234, 0x16000, v235
	v_mul_f32_e32 v252, 0xbfb8aa3b, v240
	v_mul_f32_e32 v254, v240, v240
	v_rcp_f32_e32 v254, v254
	v_pk_mul_f32 v[40:41], v[44:45], v[40:41]
	v_pk_mul_f32 v[42:43], v[46:47], v[42:43]
	v_pk_mul_f32 v[32:33], v[36:37], v[32:33]
	v_pk_mul_f32 v[34:35], v[38:39], v[34:35]
	v_pk_mul_f32 v[44:45], v[44:45], v[252:253] op_sel_hi:[1,0]
	v_pk_mul_f32 v[46:47], v[46:47], v[252:253] op_sel_hi:[1,0]
	v_pk_mul_f32 v[36:37], v[36:37], v[252:253] op_sel_hi:[1,0]
	v_pk_mul_f32 v[38:39], v[38:39], v[252:253] op_sel_hi:[1,0]
	v_exp_f32_e32 v44, v44
	v_exp_f32_e32 v45, v45
	v_exp_f32_e32 v46, v46
	v_exp_f32_e32 v47, v47
	v_exp_f32_e32 v36, v36
	v_exp_f32_e32 v37, v37
	v_exp_f32_e32 v38, v38
	v_exp_f32_e32 v39, v39
	v_pk_fma_f32 v[44:45], v[44:45], v[254:255], v[254:255] op_sel_hi:[1,0,0]
	v_pk_fma_f32 v[46:47], v[46:47], v[254:255], v[254:255] op_sel_hi:[1,0,0]
	v_pk_fma_f32 v[36:37], v[36:37], v[254:255], v[254:255] op_sel_hi:[1,0,0]
	v_pk_fma_f32 v[38:39], v[38:39], v[254:255], v[254:255] op_sel_hi:[1,0,0]
	v_rcp_f32_e32 v44, v44
	v_rcp_f32_e32 v45, v45
	v_rcp_f32_e32 v46, v46
	v_rcp_f32_e32 v47, v47
	v_rcp_f32_e32 v36, v36
	v_rcp_f32_e32 v37, v37
	v_rcp_f32_e32 v38, v38
	v_rcp_f32_e32 v39, v39
	v_pk_mul_f32 v[40:41], v[40:41], v[44:45]
	v_pk_mul_f32 v[42:43], v[42:43], v[46:47]
	v_pk_mul_f32 v[32:33], v[32:33], v[36:37]
	v_pk_mul_f32 v[34:35], v[34:35], v[38:39]
	v_cvt_pk_bf16_f32 v40, v40, v41
	v_cvt_pk_bf16_f32 v41, v42, v43
	v_cvt_pk_bf16_f32 v42, v32, v33
	v_cvt_pk_bf16_f32 v43, v34, v35
	global_store_dwordx4 v234, v[40:43], s[10:11]
	v_add_u32_e32 v235, 0x16000, v234
	v_mul_f32_e32 v252, 0xbfb8aa3b, v244
	v_mul_f32_e32 v254, v244, v244
	v_rcp_f32_e32 v254, v254
	v_pk_mul_f32 v[24:25], v[28:29], v[24:25]
	v_pk_mul_f32 v[26:27], v[30:31], v[26:27]
	v_pk_mul_f32 v[16:17], v[20:21], v[16:17]
	v_pk_mul_f32 v[18:19], v[22:23], v[18:19]
	v_pk_mul_f32 v[28:29], v[28:29], v[252:253] op_sel_hi:[1,0]
	v_pk_mul_f32 v[30:31], v[30:31], v[252:253] op_sel_hi:[1,0]
	v_pk_mul_f32 v[20:21], v[20:21], v[252:253] op_sel_hi:[1,0]
	v_pk_mul_f32 v[22:23], v[22:23], v[252:253] op_sel_hi:[1,0]
	v_exp_f32_e32 v28, v28
	v_exp_f32_e32 v29, v29
	v_exp_f32_e32 v30, v30
	v_exp_f32_e32 v31, v31
	v_exp_f32_e32 v20, v20
	v_exp_f32_e32 v21, v21
	v_exp_f32_e32 v22, v22
	v_exp_f32_e32 v23, v23
	v_pk_fma_f32 v[28:29], v[28:29], v[254:255], v[254:255] op_sel_hi:[1,0,0]
	v_pk_fma_f32 v[30:31], v[30:31], v[254:255], v[254:255] op_sel_hi:[1,0,0]
	v_pk_fma_f32 v[20:21], v[20:21], v[254:255], v[254:255] op_sel_hi:[1,0,0]
	v_pk_fma_f32 v[22:23], v[22:23], v[254:255], v[254:255] op_sel_hi:[1,0,0]
	v_rcp_f32_e32 v28, v28
	v_rcp_f32_e32 v29, v29
	v_rcp_f32_e32 v30, v30
	v_rcp_f32_e32 v31, v31
	v_rcp_f32_e32 v20, v20
	v_rcp_f32_e32 v21, v21
	v_rcp_f32_e32 v22, v22
	v_rcp_f32_e32 v23, v23
	v_pk_mul_f32 v[24:25], v[24:25], v[28:29]
	v_pk_mul_f32 v[26:27], v[26:27], v[30:31]
	v_pk_mul_f32 v[16:17], v[16:17], v[20:21]
	v_pk_mul_f32 v[18:19], v[18:19], v[22:23]
	v_cvt_pk_bf16_f32 v24, v24, v25
	v_cvt_pk_bf16_f32 v25, v26, v27
	v_cvt_pk_bf16_f32 v26, v16, v17
	v_cvt_pk_bf16_f32 v27, v18, v19
	global_store_dwordx4 v235, v[24:27], s[10:11]
	v_add_u32_e32 v234, 0x16000, v235
	v_mul_f32_e32 v252, 0xbfb8aa3b, v248
	v_mul_f32_e32 v254, v248, v248
	v_rcp_f32_e32 v254, v254
	v_pk_mul_f32 v[8:9], v[12:13], v[8:9]
	v_pk_mul_f32 v[10:11], v[14:15], v[10:11]
	v_pk_mul_f32 v[0:1], v[4:5], v[0:1]
	v_pk_mul_f32 v[2:3], v[6:7], v[2:3]
	v_pk_mul_f32 v[12:13], v[12:13], v[252:253] op_sel_hi:[1,0]
	v_pk_mul_f32 v[14:15], v[14:15], v[252:253] op_sel_hi:[1,0]
	v_pk_mul_f32 v[4:5], v[4:5], v[252:253] op_sel_hi:[1,0]
	v_pk_mul_f32 v[6:7], v[6:7], v[252:253] op_sel_hi:[1,0]
	v_exp_f32_e32 v12, v12
	v_exp_f32_e32 v13, v13
	v_exp_f32_e32 v14, v14
	v_exp_f32_e32 v15, v15
	v_exp_f32_e32 v4, v4
	v_exp_f32_e32 v5, v5
	v_exp_f32_e32 v6, v6
	v_exp_f32_e32 v7, v7
	v_pk_fma_f32 v[12:13], v[12:13], v[254:255], v[254:255] op_sel_hi:[1,0,0]
	v_pk_fma_f32 v[14:15], v[14:15], v[254:255], v[254:255] op_sel_hi:[1,0,0]
	v_pk_fma_f32 v[4:5], v[4:5], v[254:255], v[254:255] op_sel_hi:[1,0,0]
	v_pk_fma_f32 v[6:7], v[6:7], v[254:255], v[254:255] op_sel_hi:[1,0,0]
	v_rcp_f32_e32 v12, v12
	v_rcp_f32_e32 v13, v13
	v_rcp_f32_e32 v14, v14
	v_rcp_f32_e32 v15, v15
	v_rcp_f32_e32 v4, v4
	v_rcp_f32_e32 v5, v5
	v_rcp_f32_e32 v6, v6
	v_rcp_f32_e32 v7, v7
	v_pk_mul_f32 v[8:9], v[8:9], v[12:13]
	v_pk_mul_f32 v[10:11], v[10:11], v[14:15]
	v_pk_mul_f32 v[0:1], v[0:1], v[4:5]
	v_pk_mul_f32 v[2:3], v[2:3], v[6:7]
	v_cvt_pk_bf16_f32 v8, v8, v9
	v_cvt_pk_bf16_f32 v9, v10, v11
	v_cvt_pk_bf16_f32 v10, v0, v1
	v_cvt_pk_bf16_f32 v11, v2, v3
	global_store_dwordx4 v234, v[8:11], s[10:11]
.Lskip_e1_10:
	s_mov_b64 s[6:7], -1
	s_cbranch_vccnz .LBB0_1093
	s_andn2_b64 vcc, exec, s[8:9]
	s_cbranch_vccnz .LBB0_1092
	s_branch .LBB0_1092
